# scan loop: 59 compiler-conservative s_nop 0 between DPP asm blocks removed per chunk, the two-nop VALU->MFMA pads merged into one s_nop 1
# baseline (speedup 1.0000x reference)
.LBB0_583:
	s_and_b32 s48, s16, 1
	v_lshl_add_u32 v21, s48, 9, v135
	ds_read_b128 v[24:27], v21
	ds_read_b128 v[28:31], v21 offset:16
	v_fmac_f32_dpp v224, v229, v232 row_newbcast:15 row_mask:0xf bank_mask:0xf bound_ctrl:1
	s_mul_i32 s52, s48, 0x6000
	v_fmac_f32_dpp v224, v230, v19 row_newbcast:15 row_mask:0xf bank_mask:0xf bound_ctrl:1
	s_add_i32 s17, s52, 0
	v_add3_u32 v19, s17, v157, v72
	v_lshl_add_u32 v21, v73, 2, s17
	ds_read2st64_b32 v[32:33], v19 offset0:80 offset1:81
	ds_read2st64_b32 v[34:35], v21 offset0:16 offset1:17
	ds_read2st64_b32 v[36:37], v21 offset0:32 offset1:33
	ds_read2st64_b32 v[38:39], v21 offset0:48 offset1:49
	ds_read2st64_b32 v[40:41], v21 offset0:64 offset1:65
	s_waitcnt lgkmcnt(6)
	v_mov_b32_e32 v42, v24
	s_waitcnt lgkmcnt(5)
	v_mov_b32_e32 v43, v28
	v_mov_b32_e32 v44, v26
	v_mov_b32_e32 v45, v30
	v_mov_b32_e32 v28, v25
	v_mov_b32_e32 v30, v27
	v_pk_add_f32 v[24:25], v[42:43], v[44:45]
	v_pk_add_f32 v[26:27], v[28:29], v[30:31]
	s_waitcnt lgkmcnt(3)
	v_mul_f32_dpp v42, v34, v17 row_newbcast:0 row_mask:0xf bank_mask:0xf bound_ctrl:1
	v_add_f32_e32 v23, v24, v25
	v_add_f32_e32 v24, v26, v27
	v_mul_f32_dpp v25, v34, v16 row_newbcast:1 row_mask:0xf bank_mask:0xf bound_ctrl:1
	v_fmac_f32_dpp v42, v34, v15 row_newbcast:2 row_mask:0xf bank_mask:0xf bound_ctrl:1
	v_fmac_f32_dpp v25, v34, v14 row_newbcast:3 row_mask:0xf bank_mask:0xf bound_ctrl:1
	v_fmac_f32_dpp v42, v34, v13 row_newbcast:4 row_mask:0xf bank_mask:0xf bound_ctrl:1
	v_xor_b32_e32 v229, 0x80000000, v23
	v_fmac_f32_dpp v25, v34, v12 row_newbcast:5 row_mask:0xf bank_mask:0xf bound_ctrl:1
	v_fmac_f32_dpp v42, v34, v11 row_newbcast:6 row_mask:0xf bank_mask:0xf bound_ctrl:1
	v_fmac_f32_dpp v25, v34, v10 row_newbcast:7 row_mask:0xf bank_mask:0xf bound_ctrl:1
	v_fmac_f32_dpp v42, v34, v9 row_newbcast:8 row_mask:0xf bank_mask:0xf bound_ctrl:1
	v_xor_b32_e32 v230, 0x80000000, v24
	v_fmac_f32_dpp v25, v34, v8 row_newbcast:9 row_mask:0xf bank_mask:0xf bound_ctrl:1
	v_fmac_f32_dpp v42, v34, v7 row_newbcast:10 row_mask:0xf bank_mask:0xf bound_ctrl:1
	v_fmac_f32_dpp v25, v34, v6 row_newbcast:11 row_mask:0xf bank_mask:0xf bound_ctrl:1
	v_fmac_f32_dpp v42, v34, v5 row_newbcast:12 row_mask:0xf bank_mask:0xf bound_ctrl:1
	v_fmac_f32_dpp v25, v34, v4 row_newbcast:13 row_mask:0xf bank_mask:0xf bound_ctrl:1
	v_fmac_f32_dpp v42, v34, v3 row_newbcast:14 row_mask:0xf bank_mask:0xf bound_ctrl:1
	v_fmac_f32_dpp v25, v34, v2 row_newbcast:15 row_mask:0xf bank_mask:0xf bound_ctrl:1
	s_waitcnt lgkmcnt(2)
	v_fmac_f32_dpp v17, v36, v224 row_newbcast:0 row_mask:0xf bank_mask:0xf bound_ctrl:1
	v_fmac_f32_dpp v16, v36, v224 row_newbcast:1 row_mask:0xf bank_mask:0xf bound_ctrl:1
	v_fmac_f32_dpp v15, v36, v224 row_newbcast:2 row_mask:0xf bank_mask:0xf bound_ctrl:1
	v_fmac_f32_dpp v14, v36, v224 row_newbcast:3 row_mask:0xf bank_mask:0xf bound_ctrl:1
	v_fmac_f32_dpp v13, v36, v224 row_newbcast:4 row_mask:0xf bank_mask:0xf bound_ctrl:1
	v_fmac_f32_dpp v12, v36, v224 row_newbcast:5 row_mask:0xf bank_mask:0xf bound_ctrl:1
	v_fmac_f32_dpp v11, v36, v224 row_newbcast:6 row_mask:0xf bank_mask:0xf bound_ctrl:1
	v_fmac_f32_dpp v10, v36, v224 row_newbcast:7 row_mask:0xf bank_mask:0xf bound_ctrl:1
	v_fmac_f32_dpp v9, v36, v224 row_newbcast:8 row_mask:0xf bank_mask:0xf bound_ctrl:1
	v_fmac_f32_dpp v8, v36, v224 row_newbcast:9 row_mask:0xf bank_mask:0xf bound_ctrl:1
	v_fmac_f32_dpp v7, v36, v224 row_newbcast:10 row_mask:0xf bank_mask:0xf bound_ctrl:1
	v_fmac_f32_dpp v6, v36, v224 row_newbcast:11 row_mask:0xf bank_mask:0xf bound_ctrl:1
	v_fmac_f32_dpp v5, v36, v224 row_newbcast:12 row_mask:0xf bank_mask:0xf bound_ctrl:1
	v_fmac_f32_dpp v4, v36, v224 row_newbcast:13 row_mask:0xf bank_mask:0xf bound_ctrl:1
	v_fmac_f32_dpp v3, v36, v224 row_newbcast:14 row_mask:0xf bank_mask:0xf bound_ctrl:1
	v_fmac_f32_dpp v2, v36, v224 row_newbcast:15 row_mask:0xf bank_mask:0xf bound_ctrl:1
	v_add_f32 v42, v42, v25
	v_lshl_add_u32 v22, s48, 15, v134
	s_nop 1
	v_mfma_f32_16x16x4_f32 v[232:235], v228, v42, 0
	s_waitcnt lgkmcnt(1)
	v_fmac_f32_dpp v17, v38, v32 row_newbcast:0 row_mask:0xf bank_mask:0xf bound_ctrl:1
	v_fmac_f32_dpp v16, v38, v32 row_newbcast:1 row_mask:0xf bank_mask:0xf bound_ctrl:1
	v_fmac_f32_dpp v15, v38, v32 row_newbcast:2 row_mask:0xf bank_mask:0xf bound_ctrl:1
	v_fmac_f32_dpp v14, v38, v32 row_newbcast:3 row_mask:0xf bank_mask:0xf bound_ctrl:1
	v_fmac_f32_dpp v13, v38, v32 row_newbcast:4 row_mask:0xf bank_mask:0xf bound_ctrl:1
	v_fmac_f32_dpp v12, v38, v32 row_newbcast:5 row_mask:0xf bank_mask:0xf bound_ctrl:1
	v_fmac_f32_dpp v11, v38, v32 row_newbcast:6 row_mask:0xf bank_mask:0xf bound_ctrl:1
	v_fmac_f32_dpp v10, v38, v32 row_newbcast:7 row_mask:0xf bank_mask:0xf bound_ctrl:1
	v_fmac_f32_dpp v9, v38, v32 row_newbcast:8 row_mask:0xf bank_mask:0xf bound_ctrl:1
	v_fmac_f32_dpp v8, v38, v32 row_newbcast:9 row_mask:0xf bank_mask:0xf bound_ctrl:1
	v_fmac_f32_dpp v7, v38, v32 row_newbcast:10 row_mask:0xf bank_mask:0xf bound_ctrl:1
	v_fmac_f32_dpp v6, v38, v32 row_newbcast:11 row_mask:0xf bank_mask:0xf bound_ctrl:1
	v_fmac_f32_dpp v5, v38, v32 row_newbcast:12 row_mask:0xf bank_mask:0xf bound_ctrl:1
	v_fmac_f32_dpp v4, v38, v32 row_newbcast:13 row_mask:0xf bank_mask:0xf bound_ctrl:1
	v_fmac_f32_dpp v3, v38, v32 row_newbcast:14 row_mask:0xf bank_mask:0xf bound_ctrl:1
	v_fmac_f32_dpp v2, v38, v32 row_newbcast:15 row_mask:0xf bank_mask:0xf bound_ctrl:1
	s_waitcnt lgkmcnt(0)
	v_mul_f32_dpp v24, v40, v17 row_newbcast:0 row_mask:0xf bank_mask:0xf bound_ctrl:1
	v_mul_f32_dpp v25, v40, v16 row_newbcast:1 row_mask:0xf bank_mask:0xf bound_ctrl:1
	v_fmac_f32_dpp v24, v40, v15 row_newbcast:2 row_mask:0xf bank_mask:0xf bound_ctrl:1
	v_fmac_f32_dpp v25, v40, v14 row_newbcast:3 row_mask:0xf bank_mask:0xf bound_ctrl:1
	v_fmac_f32_dpp v24, v40, v13 row_newbcast:4 row_mask:0xf bank_mask:0xf bound_ctrl:1
	v_fmac_f32_dpp v25, v40, v12 row_newbcast:5 row_mask:0xf bank_mask:0xf bound_ctrl:1
	v_fmac_f32_dpp v24, v40, v11 row_newbcast:6 row_mask:0xf bank_mask:0xf bound_ctrl:1
	v_fmac_f32_dpp v25, v40, v10 row_newbcast:7 row_mask:0xf bank_mask:0xf bound_ctrl:1
	v_add_u32_e32 v20, 0xc000, v22
	v_fmac_f32_dpp v24, v40, v9 row_newbcast:8 row_mask:0xf bank_mask:0xf bound_ctrl:1
	v_fmac_f32_dpp v25, v40, v8 row_newbcast:9 row_mask:0xf bank_mask:0xf bound_ctrl:1
	v_fmac_f32_dpp v24, v40, v7 row_newbcast:10 row_mask:0xf bank_mask:0xf bound_ctrl:1
	v_fmac_f32_dpp v25, v40, v6 row_newbcast:11 row_mask:0xf bank_mask:0xf bound_ctrl:1
	s_add_i32 s16, s16, 1
	v_fmac_f32_dpp v24, v40, v5 row_newbcast:12 row_mask:0xf bank_mask:0xf bound_ctrl:1
	v_fmac_f32_dpp v25, v40, v4 row_newbcast:13 row_mask:0xf bank_mask:0xf bound_ctrl:1
	v_fmac_f32_dpp v24, v40, v3 row_newbcast:14 row_mask:0xf bank_mask:0xf bound_ctrl:1
	v_fmac_f32_dpp v25, v40, v2 row_newbcast:15 row_mask:0xf bank_mask:0xf bound_ctrl:1
	ds_read_b32 v36, v19 offset:20992
	ds_read2st64_b32 v[26:27], v21 offset0:18 offset1:34
	ds_read2st64_b32 v[28:29], v21 offset0:50 offset1:66
	v_mul_f32_dpp v38, v35, v17 row_newbcast:0 row_mask:0xf bank_mask:0xf bound_ctrl:1
	v_mul_f32_dpp v31, v35, v16 row_newbcast:1 row_mask:0xf bank_mask:0xf bound_ctrl:1
	v_fmac_f32_dpp v38, v35, v15 row_newbcast:2 row_mask:0xf bank_mask:0xf bound_ctrl:1
	v_fmac_f32_dpp v31, v35, v14 row_newbcast:3 row_mask:0xf bank_mask:0xf bound_ctrl:1
	v_fmac_f32_dpp v232, v229, v224 row_newbcast:0 row_mask:0xf bank_mask:0xf bound_ctrl:1
	v_fmac_f32_dpp v38, v35, v13 row_newbcast:4 row_mask:0xf bank_mask:0xf bound_ctrl:1
	v_fmac_f32_dpp v31, v35, v12 row_newbcast:5 row_mask:0xf bank_mask:0xf bound_ctrl:1
	v_fmac_f32_dpp v38, v35, v11 row_newbcast:6 row_mask:0xf bank_mask:0xf bound_ctrl:1
	v_fmac_f32_dpp v31, v35, v10 row_newbcast:7 row_mask:0xf bank_mask:0xf bound_ctrl:1
	v_fmac_f32_dpp v232, v230, v32 row_newbcast:0 row_mask:0xf bank_mask:0xf bound_ctrl:1
	v_fmac_f32_dpp v38, v35, v9 row_newbcast:8 row_mask:0xf bank_mask:0xf bound_ctrl:1
	v_fmac_f32_dpp v31, v35, v8 row_newbcast:9 row_mask:0xf bank_mask:0xf bound_ctrl:1
	v_fmac_f32_dpp v38, v35, v7 row_newbcast:10 row_mask:0xf bank_mask:0xf bound_ctrl:1
	v_fmac_f32_dpp v31, v35, v6 row_newbcast:11 row_mask:0xf bank_mask:0xf bound_ctrl:1
	s_cmpk_lg_i32 s16, 0x210
	v_fmac_f32_dpp v38, v35, v5 row_newbcast:12 row_mask:0xf bank_mask:0xf bound_ctrl:1
	v_fmac_f32_dpp v31, v35, v4 row_newbcast:13 row_mask:0xf bank_mask:0xf bound_ctrl:1
	v_fmac_f32_dpp v38, v35, v3 row_newbcast:14 row_mask:0xf bank_mask:0xf bound_ctrl:1
	v_fmac_f32_dpp v31, v35, v2 row_newbcast:15 row_mask:0xf bank_mask:0xf bound_ctrl:1
	v_fmac_f32_dpp v17, v37, v232 row_newbcast:0 row_mask:0xf bank_mask:0xf bound_ctrl:1
	v_fmac_f32_dpp v16, v37, v232 row_newbcast:1 row_mask:0xf bank_mask:0xf bound_ctrl:1
	v_fmac_f32_dpp v15, v37, v232 row_newbcast:2 row_mask:0xf bank_mask:0xf bound_ctrl:1
	v_fmac_f32_dpp v14, v37, v232 row_newbcast:3 row_mask:0xf bank_mask:0xf bound_ctrl:1
	v_fmac_f32_dpp v13, v37, v232 row_newbcast:4 row_mask:0xf bank_mask:0xf bound_ctrl:1
	v_fmac_f32_dpp v12, v37, v232 row_newbcast:5 row_mask:0xf bank_mask:0xf bound_ctrl:1
	v_fmac_f32_dpp v11, v37, v232 row_newbcast:6 row_mask:0xf bank_mask:0xf bound_ctrl:1
	v_fmac_f32_dpp v10, v37, v232 row_newbcast:7 row_mask:0xf bank_mask:0xf bound_ctrl:1
	v_fmac_f32_dpp v9, v37, v232 row_newbcast:8 row_mask:0xf bank_mask:0xf bound_ctrl:1
	v_fmac_f32_dpp v8, v37, v232 row_newbcast:9 row_mask:0xf bank_mask:0xf bound_ctrl:1
	v_fmac_f32_dpp v7, v37, v232 row_newbcast:10 row_mask:0xf bank_mask:0xf bound_ctrl:1
	v_fmac_f32_dpp v6, v37, v232 row_newbcast:11 row_mask:0xf bank_mask:0xf bound_ctrl:1
	v_fmac_f32_dpp v5, v37, v232 row_newbcast:12 row_mask:0xf bank_mask:0xf bound_ctrl:1
	v_fmac_f32_dpp v4, v37, v232 row_newbcast:13 row_mask:0xf bank_mask:0xf bound_ctrl:1
	v_fmac_f32_dpp v3, v37, v232 row_newbcast:14 row_mask:0xf bank_mask:0xf bound_ctrl:1
	v_fmac_f32_dpp v2, v37, v232 row_newbcast:15 row_mask:0xf bank_mask:0xf bound_ctrl:1
	v_add_f32 v38, v38, v31
	s_nop 1
	v_mfma_f32_16x16x4_f32 v[224:227], v228, v38, 0
	ds_write_b64 v22, v[24:25] offset:49152
	v_fmac_f32_dpp v17, v39, v33 row_newbcast:0 row_mask:0xf bank_mask:0xf bound_ctrl:1
	v_fmac_f32_dpp v16, v39, v33 row_newbcast:1 row_mask:0xf bank_mask:0xf bound_ctrl:1
	v_fmac_f32_dpp v15, v39, v33 row_newbcast:2 row_mask:0xf bank_mask:0xf bound_ctrl:1
	v_fmac_f32_dpp v14, v39, v33 row_newbcast:3 row_mask:0xf bank_mask:0xf bound_ctrl:1
	v_fmac_f32_dpp v13, v39, v33 row_newbcast:4 row_mask:0xf bank_mask:0xf bound_ctrl:1
	v_fmac_f32_dpp v12, v39, v33 row_newbcast:5 row_mask:0xf bank_mask:0xf bound_ctrl:1
	v_fmac_f32_dpp v11, v39, v33 row_newbcast:6 row_mask:0xf bank_mask:0xf bound_ctrl:1
	v_fmac_f32_dpp v10, v39, v33 row_newbcast:7 row_mask:0xf bank_mask:0xf bound_ctrl:1
	v_fmac_f32_dpp v9, v39, v33 row_newbcast:8 row_mask:0xf bank_mask:0xf bound_ctrl:1
	v_fmac_f32_dpp v8, v39, v33 row_newbcast:9 row_mask:0xf bank_mask:0xf bound_ctrl:1
	v_fmac_f32_dpp v7, v39, v33 row_newbcast:10 row_mask:0xf bank_mask:0xf bound_ctrl:1
	v_fmac_f32_dpp v6, v39, v33 row_newbcast:11 row_mask:0xf bank_mask:0xf bound_ctrl:1
	v_fmac_f32_dpp v5, v39, v33 row_newbcast:12 row_mask:0xf bank_mask:0xf bound_ctrl:1
	v_fmac_f32_dpp v4, v39, v33 row_newbcast:13 row_mask:0xf bank_mask:0xf bound_ctrl:1
	v_fmac_f32_dpp v3, v39, v33 row_newbcast:14 row_mask:0xf bank_mask:0xf bound_ctrl:1
	v_fmac_f32_dpp v2, v39, v33 row_newbcast:15 row_mask:0xf bank_mask:0xf bound_ctrl:1
	v_mul_f32_dpp v24, v41, v17 row_newbcast:0 row_mask:0xf bank_mask:0xf bound_ctrl:1
	v_mul_f32_dpp v25, v41, v16 row_newbcast:1 row_mask:0xf bank_mask:0xf bound_ctrl:1
	v_fmac_f32_dpp v24, v41, v15 row_newbcast:2 row_mask:0xf bank_mask:0xf bound_ctrl:1
	v_fmac_f32_dpp v25, v41, v14 row_newbcast:3 row_mask:0xf bank_mask:0xf bound_ctrl:1
	v_fmac_f32_dpp v24, v41, v13 row_newbcast:4 row_mask:0xf bank_mask:0xf bound_ctrl:1
	v_fmac_f32_dpp v25, v41, v12 row_newbcast:5 row_mask:0xf bank_mask:0xf bound_ctrl:1
	v_fmac_f32_dpp v24, v41, v11 row_newbcast:6 row_mask:0xf bank_mask:0xf bound_ctrl:1
	v_fmac_f32_dpp v25, v41, v10 row_newbcast:7 row_mask:0xf bank_mask:0xf bound_ctrl:1
	v_fmac_f32_dpp v24, v41, v9 row_newbcast:8 row_mask:0xf bank_mask:0xf bound_ctrl:1
	v_fmac_f32_dpp v25, v41, v8 row_newbcast:9 row_mask:0xf bank_mask:0xf bound_ctrl:1
	v_fmac_f32_dpp v24, v41, v7 row_newbcast:10 row_mask:0xf bank_mask:0xf bound_ctrl:1
	v_fmac_f32_dpp v25, v41, v6 row_newbcast:11 row_mask:0xf bank_mask:0xf bound_ctrl:1
	v_fmac_f32_dpp v24, v41, v5 row_newbcast:12 row_mask:0xf bank_mask:0xf bound_ctrl:1
	v_fmac_f32_dpp v25, v41, v4 row_newbcast:13 row_mask:0xf bank_mask:0xf bound_ctrl:1
	v_fmac_f32_dpp v24, v41, v3 row_newbcast:14 row_mask:0xf bank_mask:0xf bound_ctrl:1
	v_fmac_f32_dpp v25, v41, v2 row_newbcast:15 row_mask:0xf bank_mask:0xf bound_ctrl:1
	s_waitcnt lgkmcnt(0)
	ds_read_b32 v37, v19 offset:21248
	ds_read2st64_b32 v[30:31], v21 offset0:19 offset1:35
	ds_read2st64_b32 v[34:35], v21 offset0:51 offset1:67
	v_mul_f32_dpp v39, v26, v17 row_newbcast:0 row_mask:0xf bank_mask:0xf bound_ctrl:1
	v_mul_f32_dpp v32, v26, v16 row_newbcast:1 row_mask:0xf bank_mask:0xf bound_ctrl:1
	v_fmac_f32_dpp v39, v26, v15 row_newbcast:2 row_mask:0xf bank_mask:0xf bound_ctrl:1
	v_fmac_f32_dpp v32, v26, v14 row_newbcast:3 row_mask:0xf bank_mask:0xf bound_ctrl:1
	v_fmac_f32_dpp v224, v229, v232 row_newbcast:1 row_mask:0xf bank_mask:0xf bound_ctrl:1
	v_fmac_f32_dpp v39, v26, v13 row_newbcast:4 row_mask:0xf bank_mask:0xf bound_ctrl:1
	v_fmac_f32_dpp v32, v26, v12 row_newbcast:5 row_mask:0xf bank_mask:0xf bound_ctrl:1
	v_fmac_f32_dpp v39, v26, v11 row_newbcast:6 row_mask:0xf bank_mask:0xf bound_ctrl:1
	v_fmac_f32_dpp v32, v26, v10 row_newbcast:7 row_mask:0xf bank_mask:0xf bound_ctrl:1
	v_fmac_f32_dpp v224, v230, v33 row_newbcast:1 row_mask:0xf bank_mask:0xf bound_ctrl:1
	v_fmac_f32_dpp v39, v26, v9 row_newbcast:8 row_mask:0xf bank_mask:0xf bound_ctrl:1
	v_fmac_f32_dpp v32, v26, v8 row_newbcast:9 row_mask:0xf bank_mask:0xf bound_ctrl:1
	v_fmac_f32_dpp v39, v26, v7 row_newbcast:10 row_mask:0xf bank_mask:0xf bound_ctrl:1
	v_fmac_f32_dpp v32, v26, v6 row_newbcast:11 row_mask:0xf bank_mask:0xf bound_ctrl:1
	v_fmac_f32_dpp v39, v26, v5 row_newbcast:12 row_mask:0xf bank_mask:0xf bound_ctrl:1
	v_fmac_f32_dpp v32, v26, v4 row_newbcast:13 row_mask:0xf bank_mask:0xf bound_ctrl:1
	v_fmac_f32_dpp v39, v26, v3 row_newbcast:14 row_mask:0xf bank_mask:0xf bound_ctrl:1
	v_fmac_f32_dpp v32, v26, v2 row_newbcast:15 row_mask:0xf bank_mask:0xf bound_ctrl:1
	v_fmac_f32_dpp v17, v27, v224 row_newbcast:0 row_mask:0xf bank_mask:0xf bound_ctrl:1
	v_fmac_f32_dpp v16, v27, v224 row_newbcast:1 row_mask:0xf bank_mask:0xf bound_ctrl:1
	v_fmac_f32_dpp v15, v27, v224 row_newbcast:2 row_mask:0xf bank_mask:0xf bound_ctrl:1
	v_fmac_f32_dpp v14, v27, v224 row_newbcast:3 row_mask:0xf bank_mask:0xf bound_ctrl:1
	v_fmac_f32_dpp v13, v27, v224 row_newbcast:4 row_mask:0xf bank_mask:0xf bound_ctrl:1
	v_fmac_f32_dpp v12, v27, v224 row_newbcast:5 row_mask:0xf bank_mask:0xf bound_ctrl:1
	v_fmac_f32_dpp v11, v27, v224 row_newbcast:6 row_mask:0xf bank_mask:0xf bound_ctrl:1
	v_fmac_f32_dpp v10, v27, v224 row_newbcast:7 row_mask:0xf bank_mask:0xf bound_ctrl:1
	v_fmac_f32_dpp v9, v27, v224 row_newbcast:8 row_mask:0xf bank_mask:0xf bound_ctrl:1
	v_fmac_f32_dpp v8, v27, v224 row_newbcast:9 row_mask:0xf bank_mask:0xf bound_ctrl:1
	v_fmac_f32_dpp v7, v27, v224 row_newbcast:10 row_mask:0xf bank_mask:0xf bound_ctrl:1
	v_fmac_f32_dpp v6, v27, v224 row_newbcast:11 row_mask:0xf bank_mask:0xf bound_ctrl:1
	v_fmac_f32_dpp v5, v27, v224 row_newbcast:12 row_mask:0xf bank_mask:0xf bound_ctrl:1
	v_fmac_f32_dpp v4, v27, v224 row_newbcast:13 row_mask:0xf bank_mask:0xf bound_ctrl:1
	v_fmac_f32_dpp v3, v27, v224 row_newbcast:14 row_mask:0xf bank_mask:0xf bound_ctrl:1
	v_fmac_f32_dpp v2, v27, v224 row_newbcast:15 row_mask:0xf bank_mask:0xf bound_ctrl:1
	v_add_f32 v39, v39, v32
	s_nop 1
	v_mfma_f32_16x16x4_f32 v[232:235], v228, v39, 0
	ds_write_b64 v22, v[24:25] offset:51200
	v_fmac_f32_dpp v17, v28, v36 row_newbcast:0 row_mask:0xf bank_mask:0xf bound_ctrl:1
	v_fmac_f32_dpp v16, v28, v36 row_newbcast:1 row_mask:0xf bank_mask:0xf bound_ctrl:1
	v_fmac_f32_dpp v15, v28, v36 row_newbcast:2 row_mask:0xf bank_mask:0xf bound_ctrl:1
	v_fmac_f32_dpp v14, v28, v36 row_newbcast:3 row_mask:0xf bank_mask:0xf bound_ctrl:1
	v_fmac_f32_dpp v13, v28, v36 row_newbcast:4 row_mask:0xf bank_mask:0xf bound_ctrl:1
	v_fmac_f32_dpp v12, v28, v36 row_newbcast:5 row_mask:0xf bank_mask:0xf bound_ctrl:1
	v_fmac_f32_dpp v11, v28, v36 row_newbcast:6 row_mask:0xf bank_mask:0xf bound_ctrl:1
	v_fmac_f32_dpp v10, v28, v36 row_newbcast:7 row_mask:0xf bank_mask:0xf bound_ctrl:1
	v_fmac_f32_dpp v9, v28, v36 row_newbcast:8 row_mask:0xf bank_mask:0xf bound_ctrl:1
	v_fmac_f32_dpp v8, v28, v36 row_newbcast:9 row_mask:0xf bank_mask:0xf bound_ctrl:1
	v_fmac_f32_dpp v7, v28, v36 row_newbcast:10 row_mask:0xf bank_mask:0xf bound_ctrl:1
	v_fmac_f32_dpp v6, v28, v36 row_newbcast:11 row_mask:0xf bank_mask:0xf bound_ctrl:1
	v_fmac_f32_dpp v5, v28, v36 row_newbcast:12 row_mask:0xf bank_mask:0xf bound_ctrl:1
	v_fmac_f32_dpp v4, v28, v36 row_newbcast:13 row_mask:0xf bank_mask:0xf bound_ctrl:1
	v_fmac_f32_dpp v3, v28, v36 row_newbcast:14 row_mask:0xf bank_mask:0xf bound_ctrl:1
	v_fmac_f32_dpp v2, v28, v36 row_newbcast:15 row_mask:0xf bank_mask:0xf bound_ctrl:1
	v_mul_f32_dpp v24, v29, v17 row_newbcast:0 row_mask:0xf bank_mask:0xf bound_ctrl:1
	v_mul_f32_dpp v25, v29, v16 row_newbcast:1 row_mask:0xf bank_mask:0xf bound_ctrl:1
	v_fmac_f32_dpp v24, v29, v15 row_newbcast:2 row_mask:0xf bank_mask:0xf bound_ctrl:1
	v_fmac_f32_dpp v25, v29, v14 row_newbcast:3 row_mask:0xf bank_mask:0xf bound_ctrl:1
	v_fmac_f32_dpp v24, v29, v13 row_newbcast:4 row_mask:0xf bank_mask:0xf bound_ctrl:1
	v_fmac_f32_dpp v25, v29, v12 row_newbcast:5 row_mask:0xf bank_mask:0xf bound_ctrl:1
	v_fmac_f32_dpp v24, v29, v11 row_newbcast:6 row_mask:0xf bank_mask:0xf bound_ctrl:1
	v_fmac_f32_dpp v25, v29, v10 row_newbcast:7 row_mask:0xf bank_mask:0xf bound_ctrl:1
	v_fmac_f32_dpp v24, v29, v9 row_newbcast:8 row_mask:0xf bank_mask:0xf bound_ctrl:1
	v_fmac_f32_dpp v25, v29, v8 row_newbcast:9 row_mask:0xf bank_mask:0xf bound_ctrl:1
	v_fmac_f32_dpp v24, v29, v7 row_newbcast:10 row_mask:0xf bank_mask:0xf bound_ctrl:1
	v_fmac_f32_dpp v25, v29, v6 row_newbcast:11 row_mask:0xf bank_mask:0xf bound_ctrl:1
	v_fmac_f32_dpp v24, v29, v5 row_newbcast:12 row_mask:0xf bank_mask:0xf bound_ctrl:1
	v_fmac_f32_dpp v25, v29, v4 row_newbcast:13 row_mask:0xf bank_mask:0xf bound_ctrl:1
	v_fmac_f32_dpp v24, v29, v3 row_newbcast:14 row_mask:0xf bank_mask:0xf bound_ctrl:1
	v_fmac_f32_dpp v25, v29, v2 row_newbcast:15 row_mask:0xf bank_mask:0xf bound_ctrl:1
	s_waitcnt lgkmcnt(0)
	ds_read_b32 v40, v19 offset:21504
	ds_read2st64_b32 v[26:27], v21 offset0:20 offset1:36
	ds_read2st64_b32 v[28:29], v21 offset0:52 offset1:68
	v_mul_f32_dpp v41, v30, v17 row_newbcast:0 row_mask:0xf bank_mask:0xf bound_ctrl:1
	v_mul_f32_dpp v32, v30, v16 row_newbcast:1 row_mask:0xf bank_mask:0xf bound_ctrl:1
	v_fmac_f32_dpp v41, v30, v15 row_newbcast:2 row_mask:0xf bank_mask:0xf bound_ctrl:1
	v_fmac_f32_dpp v32, v30, v14 row_newbcast:3 row_mask:0xf bank_mask:0xf bound_ctrl:1
	v_fmac_f32_dpp v232, v229, v224 row_newbcast:2 row_mask:0xf bank_mask:0xf bound_ctrl:1
	v_fmac_f32_dpp v41, v30, v13 row_newbcast:4 row_mask:0xf bank_mask:0xf bound_ctrl:1
	v_fmac_f32_dpp v32, v30, v12 row_newbcast:5 row_mask:0xf bank_mask:0xf bound_ctrl:1
	v_fmac_f32_dpp v41, v30, v11 row_newbcast:6 row_mask:0xf bank_mask:0xf bound_ctrl:1
	v_fmac_f32_dpp v32, v30, v10 row_newbcast:7 row_mask:0xf bank_mask:0xf bound_ctrl:1
	v_fmac_f32_dpp v232, v230, v36 row_newbcast:2 row_mask:0xf bank_mask:0xf bound_ctrl:1
	v_fmac_f32_dpp v41, v30, v9 row_newbcast:8 row_mask:0xf bank_mask:0xf bound_ctrl:1
	v_fmac_f32_dpp v32, v30, v8 row_newbcast:9 row_mask:0xf bank_mask:0xf bound_ctrl:1
	v_fmac_f32_dpp v41, v30, v7 row_newbcast:10 row_mask:0xf bank_mask:0xf bound_ctrl:1
	v_fmac_f32_dpp v32, v30, v6 row_newbcast:11 row_mask:0xf bank_mask:0xf bound_ctrl:1
	v_fmac_f32_dpp v41, v30, v5 row_newbcast:12 row_mask:0xf bank_mask:0xf bound_ctrl:1
	v_fmac_f32_dpp v32, v30, v4 row_newbcast:13 row_mask:0xf bank_mask:0xf bound_ctrl:1
	v_fmac_f32_dpp v41, v30, v3 row_newbcast:14 row_mask:0xf bank_mask:0xf bound_ctrl:1
	v_fmac_f32_dpp v32, v30, v2 row_newbcast:15 row_mask:0xf bank_mask:0xf bound_ctrl:1
	v_fmac_f32_dpp v17, v31, v232 row_newbcast:0 row_mask:0xf bank_mask:0xf bound_ctrl:1
	v_fmac_f32_dpp v16, v31, v232 row_newbcast:1 row_mask:0xf bank_mask:0xf bound_ctrl:1
	v_fmac_f32_dpp v15, v31, v232 row_newbcast:2 row_mask:0xf bank_mask:0xf bound_ctrl:1
	v_fmac_f32_dpp v14, v31, v232 row_newbcast:3 row_mask:0xf bank_mask:0xf bound_ctrl:1
	v_fmac_f32_dpp v13, v31, v232 row_newbcast:4 row_mask:0xf bank_mask:0xf bound_ctrl:1
	v_fmac_f32_dpp v12, v31, v232 row_newbcast:5 row_mask:0xf bank_mask:0xf bound_ctrl:1
	v_fmac_f32_dpp v11, v31, v232 row_newbcast:6 row_mask:0xf bank_mask:0xf bound_ctrl:1
	v_fmac_f32_dpp v10, v31, v232 row_newbcast:7 row_mask:0xf bank_mask:0xf bound_ctrl:1
	v_fmac_f32_dpp v9, v31, v232 row_newbcast:8 row_mask:0xf bank_mask:0xf bound_ctrl:1
	v_fmac_f32_dpp v8, v31, v232 row_newbcast:9 row_mask:0xf bank_mask:0xf bound_ctrl:1
	v_fmac_f32_dpp v7, v31, v232 row_newbcast:10 row_mask:0xf bank_mask:0xf bound_ctrl:1
	v_fmac_f32_dpp v6, v31, v232 row_newbcast:11 row_mask:0xf bank_mask:0xf bound_ctrl:1
	v_fmac_f32_dpp v5, v31, v232 row_newbcast:12 row_mask:0xf bank_mask:0xf bound_ctrl:1
	v_fmac_f32_dpp v4, v31, v232 row_newbcast:13 row_mask:0xf bank_mask:0xf bound_ctrl:1
	v_fmac_f32_dpp v3, v31, v232 row_newbcast:14 row_mask:0xf bank_mask:0xf bound_ctrl:1
	v_fmac_f32_dpp v2, v31, v232 row_newbcast:15 row_mask:0xf bank_mask:0xf bound_ctrl:1
	v_add_f32 v41, v41, v32
	s_nop 1
	v_mfma_f32_16x16x4_f32 v[224:227], v228, v41, 0
	ds_write_b64 v22, v[24:25] offset:53248
	v_fmac_f32_dpp v17, v34, v37 row_newbcast:0 row_mask:0xf bank_mask:0xf bound_ctrl:1
	v_fmac_f32_dpp v16, v34, v37 row_newbcast:1 row_mask:0xf bank_mask:0xf bound_ctrl:1
	v_fmac_f32_dpp v15, v34, v37 row_newbcast:2 row_mask:0xf bank_mask:0xf bound_ctrl:1
	v_fmac_f32_dpp v14, v34, v37 row_newbcast:3 row_mask:0xf bank_mask:0xf bound_ctrl:1
	v_fmac_f32_dpp v13, v34, v37 row_newbcast:4 row_mask:0xf bank_mask:0xf bound_ctrl:1
	v_fmac_f32_dpp v12, v34, v37 row_newbcast:5 row_mask:0xf bank_mask:0xf bound_ctrl:1
	v_fmac_f32_dpp v11, v34, v37 row_newbcast:6 row_mask:0xf bank_mask:0xf bound_ctrl:1
	v_fmac_f32_dpp v10, v34, v37 row_newbcast:7 row_mask:0xf bank_mask:0xf bound_ctrl:1
	v_fmac_f32_dpp v9, v34, v37 row_newbcast:8 row_mask:0xf bank_mask:0xf bound_ctrl:1
	v_fmac_f32_dpp v8, v34, v37 row_newbcast:9 row_mask:0xf bank_mask:0xf bound_ctrl:1
	v_fmac_f32_dpp v7, v34, v37 row_newbcast:10 row_mask:0xf bank_mask:0xf bound_ctrl:1
	v_fmac_f32_dpp v6, v34, v37 row_newbcast:11 row_mask:0xf bank_mask:0xf bound_ctrl:1
	v_fmac_f32_dpp v5, v34, v37 row_newbcast:12 row_mask:0xf bank_mask:0xf bound_ctrl:1
	v_fmac_f32_dpp v4, v34, v37 row_newbcast:13 row_mask:0xf bank_mask:0xf bound_ctrl:1
	v_fmac_f32_dpp v3, v34, v37 row_newbcast:14 row_mask:0xf bank_mask:0xf bound_ctrl:1
	v_fmac_f32_dpp v2, v34, v37 row_newbcast:15 row_mask:0xf bank_mask:0xf bound_ctrl:1
	v_mul_f32_dpp v24, v35, v17 row_newbcast:0 row_mask:0xf bank_mask:0xf bound_ctrl:1
	v_mul_f32_dpp v25, v35, v16 row_newbcast:1 row_mask:0xf bank_mask:0xf bound_ctrl:1
	v_fmac_f32_dpp v24, v35, v15 row_newbcast:2 row_mask:0xf bank_mask:0xf bound_ctrl:1
	v_fmac_f32_dpp v25, v35, v14 row_newbcast:3 row_mask:0xf bank_mask:0xf bound_ctrl:1
	v_fmac_f32_dpp v24, v35, v13 row_newbcast:4 row_mask:0xf bank_mask:0xf bound_ctrl:1
	v_fmac_f32_dpp v25, v35, v12 row_newbcast:5 row_mask:0xf bank_mask:0xf bound_ctrl:1
	v_fmac_f32_dpp v24, v35, v11 row_newbcast:6 row_mask:0xf bank_mask:0xf bound_ctrl:1
	v_fmac_f32_dpp v25, v35, v10 row_newbcast:7 row_mask:0xf bank_mask:0xf bound_ctrl:1
	v_fmac_f32_dpp v24, v35, v9 row_newbcast:8 row_mask:0xf bank_mask:0xf bound_ctrl:1
	v_fmac_f32_dpp v25, v35, v8 row_newbcast:9 row_mask:0xf bank_mask:0xf bound_ctrl:1
	v_fmac_f32_dpp v24, v35, v7 row_newbcast:10 row_mask:0xf bank_mask:0xf bound_ctrl:1
	v_fmac_f32_dpp v25, v35, v6 row_newbcast:11 row_mask:0xf bank_mask:0xf bound_ctrl:1
	v_fmac_f32_dpp v24, v35, v5 row_newbcast:12 row_mask:0xf bank_mask:0xf bound_ctrl:1
	v_fmac_f32_dpp v25, v35, v4 row_newbcast:13 row_mask:0xf bank_mask:0xf bound_ctrl:1
	v_fmac_f32_dpp v24, v35, v3 row_newbcast:14 row_mask:0xf bank_mask:0xf bound_ctrl:1
	v_fmac_f32_dpp v25, v35, v2 row_newbcast:15 row_mask:0xf bank_mask:0xf bound_ctrl:1
	s_waitcnt lgkmcnt(0)
	ds_read_b32 v34, v19 offset:21760
	ds_read2st64_b32 v[30:31], v21 offset0:21 offset1:37
	ds_read2st64_b32 v[32:33], v21 offset0:53 offset1:69
	v_mul_f32_dpp v35, v26, v17 row_newbcast:0 row_mask:0xf bank_mask:0xf bound_ctrl:1
	v_mul_f32_dpp v36, v26, v16 row_newbcast:1 row_mask:0xf bank_mask:0xf bound_ctrl:1
	v_fmac_f32_dpp v35, v26, v15 row_newbcast:2 row_mask:0xf bank_mask:0xf bound_ctrl:1
	v_fmac_f32_dpp v36, v26, v14 row_newbcast:3 row_mask:0xf bank_mask:0xf bound_ctrl:1
	v_fmac_f32_dpp v224, v229, v232 row_newbcast:3 row_mask:0xf bank_mask:0xf bound_ctrl:1
	v_fmac_f32_dpp v35, v26, v13 row_newbcast:4 row_mask:0xf bank_mask:0xf bound_ctrl:1
	v_fmac_f32_dpp v36, v26, v12 row_newbcast:5 row_mask:0xf bank_mask:0xf bound_ctrl:1
	v_fmac_f32_dpp v35, v26, v11 row_newbcast:6 row_mask:0xf bank_mask:0xf bound_ctrl:1
	v_fmac_f32_dpp v36, v26, v10 row_newbcast:7 row_mask:0xf bank_mask:0xf bound_ctrl:1
	v_fmac_f32_dpp v224, v230, v37 row_newbcast:3 row_mask:0xf bank_mask:0xf bound_ctrl:1
	v_fmac_f32_dpp v35, v26, v9 row_newbcast:8 row_mask:0xf bank_mask:0xf bound_ctrl:1
	v_fmac_f32_dpp v36, v26, v8 row_newbcast:9 row_mask:0xf bank_mask:0xf bound_ctrl:1
	v_fmac_f32_dpp v35, v26, v7 row_newbcast:10 row_mask:0xf bank_mask:0xf bound_ctrl:1
	v_fmac_f32_dpp v36, v26, v6 row_newbcast:11 row_mask:0xf bank_mask:0xf bound_ctrl:1
	v_fmac_f32_dpp v35, v26, v5 row_newbcast:12 row_mask:0xf bank_mask:0xf bound_ctrl:1
	v_fmac_f32_dpp v36, v26, v4 row_newbcast:13 row_mask:0xf bank_mask:0xf bound_ctrl:1
	v_fmac_f32_dpp v35, v26, v3 row_newbcast:14 row_mask:0xf bank_mask:0xf bound_ctrl:1
	v_fmac_f32_dpp v36, v26, v2 row_newbcast:15 row_mask:0xf bank_mask:0xf bound_ctrl:1
	v_fmac_f32_dpp v17, v27, v224 row_newbcast:0 row_mask:0xf bank_mask:0xf bound_ctrl:1
	v_fmac_f32_dpp v16, v27, v224 row_newbcast:1 row_mask:0xf bank_mask:0xf bound_ctrl:1
	v_fmac_f32_dpp v15, v27, v224 row_newbcast:2 row_mask:0xf bank_mask:0xf bound_ctrl:1
	v_fmac_f32_dpp v14, v27, v224 row_newbcast:3 row_mask:0xf bank_mask:0xf bound_ctrl:1
	v_fmac_f32_dpp v13, v27, v224 row_newbcast:4 row_mask:0xf bank_mask:0xf bound_ctrl:1
	v_fmac_f32_dpp v12, v27, v224 row_newbcast:5 row_mask:0xf bank_mask:0xf bound_ctrl:1
	v_fmac_f32_dpp v11, v27, v224 row_newbcast:6 row_mask:0xf bank_mask:0xf bound_ctrl:1
	v_fmac_f32_dpp v10, v27, v224 row_newbcast:7 row_mask:0xf bank_mask:0xf bound_ctrl:1
	v_fmac_f32_dpp v9, v27, v224 row_newbcast:8 row_mask:0xf bank_mask:0xf bound_ctrl:1
	v_fmac_f32_dpp v8, v27, v224 row_newbcast:9 row_mask:0xf bank_mask:0xf bound_ctrl:1
	v_fmac_f32_dpp v7, v27, v224 row_newbcast:10 row_mask:0xf bank_mask:0xf bound_ctrl:1
	v_fmac_f32_dpp v6, v27, v224 row_newbcast:11 row_mask:0xf bank_mask:0xf bound_ctrl:1
	v_fmac_f32_dpp v5, v27, v224 row_newbcast:12 row_mask:0xf bank_mask:0xf bound_ctrl:1
	v_fmac_f32_dpp v4, v27, v224 row_newbcast:13 row_mask:0xf bank_mask:0xf bound_ctrl:1
	v_fmac_f32_dpp v3, v27, v224 row_newbcast:14 row_mask:0xf bank_mask:0xf bound_ctrl:1
	v_fmac_f32_dpp v2, v27, v224 row_newbcast:15 row_mask:0xf bank_mask:0xf bound_ctrl:1
	v_add_f32 v35, v35, v36
	s_nop 1
	v_mfma_f32_16x16x4_f32 v[232:235], v228, v35, 0
	ds_write_b64 v22, v[24:25] offset:55296
	v_fmac_f32_dpp v17, v28, v40 row_newbcast:0 row_mask:0xf bank_mask:0xf bound_ctrl:1
	v_fmac_f32_dpp v16, v28, v40 row_newbcast:1 row_mask:0xf bank_mask:0xf bound_ctrl:1
	v_fmac_f32_dpp v15, v28, v40 row_newbcast:2 row_mask:0xf bank_mask:0xf bound_ctrl:1
	v_fmac_f32_dpp v14, v28, v40 row_newbcast:3 row_mask:0xf bank_mask:0xf bound_ctrl:1
	v_fmac_f32_dpp v13, v28, v40 row_newbcast:4 row_mask:0xf bank_mask:0xf bound_ctrl:1
	v_fmac_f32_dpp v12, v28, v40 row_newbcast:5 row_mask:0xf bank_mask:0xf bound_ctrl:1
	v_fmac_f32_dpp v11, v28, v40 row_newbcast:6 row_mask:0xf bank_mask:0xf bound_ctrl:1
	v_fmac_f32_dpp v10, v28, v40 row_newbcast:7 row_mask:0xf bank_mask:0xf bound_ctrl:1
	v_fmac_f32_dpp v9, v28, v40 row_newbcast:8 row_mask:0xf bank_mask:0xf bound_ctrl:1
	v_fmac_f32_dpp v8, v28, v40 row_newbcast:9 row_mask:0xf bank_mask:0xf bound_ctrl:1
	v_fmac_f32_dpp v7, v28, v40 row_newbcast:10 row_mask:0xf bank_mask:0xf bound_ctrl:1
	v_fmac_f32_dpp v6, v28, v40 row_newbcast:11 row_mask:0xf bank_mask:0xf bound_ctrl:1
	v_fmac_f32_dpp v5, v28, v40 row_newbcast:12 row_mask:0xf bank_mask:0xf bound_ctrl:1
	v_fmac_f32_dpp v4, v28, v40 row_newbcast:13 row_mask:0xf bank_mask:0xf bound_ctrl:1
	v_fmac_f32_dpp v3, v28, v40 row_newbcast:14 row_mask:0xf bank_mask:0xf bound_ctrl:1
	v_fmac_f32_dpp v2, v28, v40 row_newbcast:15 row_mask:0xf bank_mask:0xf bound_ctrl:1
	v_mul_f32_dpp v24, v29, v17 row_newbcast:0 row_mask:0xf bank_mask:0xf bound_ctrl:1
	v_mul_f32_dpp v25, v29, v16 row_newbcast:1 row_mask:0xf bank_mask:0xf bound_ctrl:1
	v_fmac_f32_dpp v24, v29, v15 row_newbcast:2 row_mask:0xf bank_mask:0xf bound_ctrl:1
	v_fmac_f32_dpp v25, v29, v14 row_newbcast:3 row_mask:0xf bank_mask:0xf bound_ctrl:1
	v_fmac_f32_dpp v24, v29, v13 row_newbcast:4 row_mask:0xf bank_mask:0xf bound_ctrl:1
	v_fmac_f32_dpp v25, v29, v12 row_newbcast:5 row_mask:0xf bank_mask:0xf bound_ctrl:1
	v_fmac_f32_dpp v24, v29, v11 row_newbcast:6 row_mask:0xf bank_mask:0xf bound_ctrl:1
	v_fmac_f32_dpp v25, v29, v10 row_newbcast:7 row_mask:0xf bank_mask:0xf bound_ctrl:1
	v_fmac_f32_dpp v24, v29, v9 row_newbcast:8 row_mask:0xf bank_mask:0xf bound_ctrl:1
	v_fmac_f32_dpp v25, v29, v8 row_newbcast:9 row_mask:0xf bank_mask:0xf bound_ctrl:1
	v_fmac_f32_dpp v24, v29, v7 row_newbcast:10 row_mask:0xf bank_mask:0xf bound_ctrl:1
	v_fmac_f32_dpp v25, v29, v6 row_newbcast:11 row_mask:0xf bank_mask:0xf bound_ctrl:1
	v_fmac_f32_dpp v24, v29, v5 row_newbcast:12 row_mask:0xf bank_mask:0xf bound_ctrl:1
	v_fmac_f32_dpp v25, v29, v4 row_newbcast:13 row_mask:0xf bank_mask:0xf bound_ctrl:1
	v_fmac_f32_dpp v24, v29, v3 row_newbcast:14 row_mask:0xf bank_mask:0xf bound_ctrl:1
	v_fmac_f32_dpp v25, v29, v2 row_newbcast:15 row_mask:0xf bank_mask:0xf bound_ctrl:1
	s_waitcnt lgkmcnt(0)
	ds_read_b32 v36, v19 offset:22016
	ds_read2st64_b32 v[26:27], v21 offset0:22 offset1:38
	ds_read2st64_b32 v[28:29], v21 offset0:54 offset1:70
	v_mul_f32_dpp v37, v30, v17 row_newbcast:0 row_mask:0xf bank_mask:0xf bound_ctrl:1
	v_mul_f32_dpp v38, v30, v16 row_newbcast:1 row_mask:0xf bank_mask:0xf bound_ctrl:1
	v_fmac_f32_dpp v37, v30, v15 row_newbcast:2 row_mask:0xf bank_mask:0xf bound_ctrl:1
	v_fmac_f32_dpp v38, v30, v14 row_newbcast:3 row_mask:0xf bank_mask:0xf bound_ctrl:1
	v_fmac_f32_dpp v232, v229, v224 row_newbcast:4 row_mask:0xf bank_mask:0xf bound_ctrl:1
	v_fmac_f32_dpp v37, v30, v13 row_newbcast:4 row_mask:0xf bank_mask:0xf bound_ctrl:1
	v_fmac_f32_dpp v38, v30, v12 row_newbcast:5 row_mask:0xf bank_mask:0xf bound_ctrl:1
	v_fmac_f32_dpp v37, v30, v11 row_newbcast:6 row_mask:0xf bank_mask:0xf bound_ctrl:1
	v_fmac_f32_dpp v38, v30, v10 row_newbcast:7 row_mask:0xf bank_mask:0xf bound_ctrl:1
	v_fmac_f32_dpp v232, v230, v40 row_newbcast:4 row_mask:0xf bank_mask:0xf bound_ctrl:1
	v_fmac_f32_dpp v37, v30, v9 row_newbcast:8 row_mask:0xf bank_mask:0xf bound_ctrl:1
	v_fmac_f32_dpp v38, v30, v8 row_newbcast:9 row_mask:0xf bank_mask:0xf bound_ctrl:1
	v_fmac_f32_dpp v37, v30, v7 row_newbcast:10 row_mask:0xf bank_mask:0xf bound_ctrl:1
	v_fmac_f32_dpp v38, v30, v6 row_newbcast:11 row_mask:0xf bank_mask:0xf bound_ctrl:1
	v_fmac_f32_dpp v37, v30, v5 row_newbcast:12 row_mask:0xf bank_mask:0xf bound_ctrl:1
	v_fmac_f32_dpp v38, v30, v4 row_newbcast:13 row_mask:0xf bank_mask:0xf bound_ctrl:1
	v_fmac_f32_dpp v37, v30, v3 row_newbcast:14 row_mask:0xf bank_mask:0xf bound_ctrl:1
	v_fmac_f32_dpp v38, v30, v2 row_newbcast:15 row_mask:0xf bank_mask:0xf bound_ctrl:1
	v_fmac_f32_dpp v17, v31, v232 row_newbcast:0 row_mask:0xf bank_mask:0xf bound_ctrl:1
	v_fmac_f32_dpp v16, v31, v232 row_newbcast:1 row_mask:0xf bank_mask:0xf bound_ctrl:1
	v_fmac_f32_dpp v15, v31, v232 row_newbcast:2 row_mask:0xf bank_mask:0xf bound_ctrl:1
	v_fmac_f32_dpp v14, v31, v232 row_newbcast:3 row_mask:0xf bank_mask:0xf bound_ctrl:1
	v_fmac_f32_dpp v13, v31, v232 row_newbcast:4 row_mask:0xf bank_mask:0xf bound_ctrl:1
	v_fmac_f32_dpp v12, v31, v232 row_newbcast:5 row_mask:0xf bank_mask:0xf bound_ctrl:1
	v_fmac_f32_dpp v11, v31, v232 row_newbcast:6 row_mask:0xf bank_mask:0xf bound_ctrl:1
	v_fmac_f32_dpp v10, v31, v232 row_newbcast:7 row_mask:0xf bank_mask:0xf bound_ctrl:1
	v_fmac_f32_dpp v9, v31, v232 row_newbcast:8 row_mask:0xf bank_mask:0xf bound_ctrl:1
	v_fmac_f32_dpp v8, v31, v232 row_newbcast:9 row_mask:0xf bank_mask:0xf bound_ctrl:1
	v_fmac_f32_dpp v7, v31, v232 row_newbcast:10 row_mask:0xf bank_mask:0xf bound_ctrl:1
	v_fmac_f32_dpp v6, v31, v232 row_newbcast:11 row_mask:0xf bank_mask:0xf bound_ctrl:1
	v_fmac_f32_dpp v5, v31, v232 row_newbcast:12 row_mask:0xf bank_mask:0xf bound_ctrl:1
	v_fmac_f32_dpp v4, v31, v232 row_newbcast:13 row_mask:0xf bank_mask:0xf bound_ctrl:1
	v_fmac_f32_dpp v3, v31, v232 row_newbcast:14 row_mask:0xf bank_mask:0xf bound_ctrl:1
	v_fmac_f32_dpp v2, v31, v232 row_newbcast:15 row_mask:0xf bank_mask:0xf bound_ctrl:1
	v_add_f32 v37, v37, v38
	s_nop 1
	v_mfma_f32_16x16x4_f32 v[224:227], v228, v37, 0
	ds_write_b64 v22, v[24:25] offset:57344
	v_fmac_f32_dpp v17, v32, v34 row_newbcast:0 row_mask:0xf bank_mask:0xf bound_ctrl:1
	v_fmac_f32_dpp v16, v32, v34 row_newbcast:1 row_mask:0xf bank_mask:0xf bound_ctrl:1
	v_fmac_f32_dpp v15, v32, v34 row_newbcast:2 row_mask:0xf bank_mask:0xf bound_ctrl:1
	v_fmac_f32_dpp v14, v32, v34 row_newbcast:3 row_mask:0xf bank_mask:0xf bound_ctrl:1
	v_fmac_f32_dpp v13, v32, v34 row_newbcast:4 row_mask:0xf bank_mask:0xf bound_ctrl:1
	v_fmac_f32_dpp v12, v32, v34 row_newbcast:5 row_mask:0xf bank_mask:0xf bound_ctrl:1
	v_fmac_f32_dpp v11, v32, v34 row_newbcast:6 row_mask:0xf bank_mask:0xf bound_ctrl:1
	v_fmac_f32_dpp v10, v32, v34 row_newbcast:7 row_mask:0xf bank_mask:0xf bound_ctrl:1
	v_fmac_f32_dpp v9, v32, v34 row_newbcast:8 row_mask:0xf bank_mask:0xf bound_ctrl:1
	v_fmac_f32_dpp v8, v32, v34 row_newbcast:9 row_mask:0xf bank_mask:0xf bound_ctrl:1
	v_fmac_f32_dpp v7, v32, v34 row_newbcast:10 row_mask:0xf bank_mask:0xf bound_ctrl:1
	v_fmac_f32_dpp v6, v32, v34 row_newbcast:11 row_mask:0xf bank_mask:0xf bound_ctrl:1
	v_fmac_f32_dpp v5, v32, v34 row_newbcast:12 row_mask:0xf bank_mask:0xf bound_ctrl:1
	v_fmac_f32_dpp v4, v32, v34 row_newbcast:13 row_mask:0xf bank_mask:0xf bound_ctrl:1
	v_fmac_f32_dpp v3, v32, v34 row_newbcast:14 row_mask:0xf bank_mask:0xf bound_ctrl:1
	v_fmac_f32_dpp v2, v32, v34 row_newbcast:15 row_mask:0xf bank_mask:0xf bound_ctrl:1
	v_mul_f32_dpp v24, v33, v17 row_newbcast:0 row_mask:0xf bank_mask:0xf bound_ctrl:1
	v_mul_f32_dpp v25, v33, v16 row_newbcast:1 row_mask:0xf bank_mask:0xf bound_ctrl:1
	v_fmac_f32_dpp v24, v33, v15 row_newbcast:2 row_mask:0xf bank_mask:0xf bound_ctrl:1
	v_fmac_f32_dpp v25, v33, v14 row_newbcast:3 row_mask:0xf bank_mask:0xf bound_ctrl:1
	v_fmac_f32_dpp v24, v33, v13 row_newbcast:4 row_mask:0xf bank_mask:0xf bound_ctrl:1
	v_fmac_f32_dpp v25, v33, v12 row_newbcast:5 row_mask:0xf bank_mask:0xf bound_ctrl:1
	v_fmac_f32_dpp v24, v33, v11 row_newbcast:6 row_mask:0xf bank_mask:0xf bound_ctrl:1
	v_fmac_f32_dpp v25, v33, v10 row_newbcast:7 row_mask:0xf bank_mask:0xf bound_ctrl:1
	v_fmac_f32_dpp v24, v33, v9 row_newbcast:8 row_mask:0xf bank_mask:0xf bound_ctrl:1
	v_fmac_f32_dpp v25, v33, v8 row_newbcast:9 row_mask:0xf bank_mask:0xf bound_ctrl:1
	v_fmac_f32_dpp v24, v33, v7 row_newbcast:10 row_mask:0xf bank_mask:0xf bound_ctrl:1
	v_fmac_f32_dpp v25, v33, v6 row_newbcast:11 row_mask:0xf bank_mask:0xf bound_ctrl:1
	v_fmac_f32_dpp v24, v33, v5 row_newbcast:12 row_mask:0xf bank_mask:0xf bound_ctrl:1
	v_fmac_f32_dpp v25, v33, v4 row_newbcast:13 row_mask:0xf bank_mask:0xf bound_ctrl:1
	v_fmac_f32_dpp v24, v33, v3 row_newbcast:14 row_mask:0xf bank_mask:0xf bound_ctrl:1
	v_fmac_f32_dpp v25, v33, v2 row_newbcast:15 row_mask:0xf bank_mask:0xf bound_ctrl:1
	s_waitcnt lgkmcnt(0)
	ds_read_b32 v38, v19 offset:22272
	ds_read2st64_b32 v[30:31], v21 offset0:23 offset1:39
	ds_read2st64_b32 v[32:33], v21 offset0:55 offset1:71
	v_mul_f32_dpp v39, v26, v17 row_newbcast:0 row_mask:0xf bank_mask:0xf bound_ctrl:1
	v_mul_f32_dpp v40, v26, v16 row_newbcast:1 row_mask:0xf bank_mask:0xf bound_ctrl:1
	v_fmac_f32_dpp v39, v26, v15 row_newbcast:2 row_mask:0xf bank_mask:0xf bound_ctrl:1
	v_fmac_f32_dpp v40, v26, v14 row_newbcast:3 row_mask:0xf bank_mask:0xf bound_ctrl:1
	v_fmac_f32_dpp v224, v229, v232 row_newbcast:5 row_mask:0xf bank_mask:0xf bound_ctrl:1
	v_fmac_f32_dpp v39, v26, v13 row_newbcast:4 row_mask:0xf bank_mask:0xf bound_ctrl:1
	v_fmac_f32_dpp v40, v26, v12 row_newbcast:5 row_mask:0xf bank_mask:0xf bound_ctrl:1
	v_fmac_f32_dpp v39, v26, v11 row_newbcast:6 row_mask:0xf bank_mask:0xf bound_ctrl:1
	v_fmac_f32_dpp v40, v26, v10 row_newbcast:7 row_mask:0xf bank_mask:0xf bound_ctrl:1
	v_fmac_f32_dpp v224, v230, v34 row_newbcast:5 row_mask:0xf bank_mask:0xf bound_ctrl:1
	v_fmac_f32_dpp v39, v26, v9 row_newbcast:8 row_mask:0xf bank_mask:0xf bound_ctrl:1
	v_fmac_f32_dpp v40, v26, v8 row_newbcast:9 row_mask:0xf bank_mask:0xf bound_ctrl:1
	v_fmac_f32_dpp v39, v26, v7 row_newbcast:10 row_mask:0xf bank_mask:0xf bound_ctrl:1
	v_fmac_f32_dpp v40, v26, v6 row_newbcast:11 row_mask:0xf bank_mask:0xf bound_ctrl:1
	v_fmac_f32_dpp v39, v26, v5 row_newbcast:12 row_mask:0xf bank_mask:0xf bound_ctrl:1
	v_fmac_f32_dpp v40, v26, v4 row_newbcast:13 row_mask:0xf bank_mask:0xf bound_ctrl:1
	v_fmac_f32_dpp v39, v26, v3 row_newbcast:14 row_mask:0xf bank_mask:0xf bound_ctrl:1
	v_fmac_f32_dpp v40, v26, v2 row_newbcast:15 row_mask:0xf bank_mask:0xf bound_ctrl:1
	v_fmac_f32_dpp v17, v27, v224 row_newbcast:0 row_mask:0xf bank_mask:0xf bound_ctrl:1
	v_fmac_f32_dpp v16, v27, v224 row_newbcast:1 row_mask:0xf bank_mask:0xf bound_ctrl:1
	v_fmac_f32_dpp v15, v27, v224 row_newbcast:2 row_mask:0xf bank_mask:0xf bound_ctrl:1
	v_fmac_f32_dpp v14, v27, v224 row_newbcast:3 row_mask:0xf bank_mask:0xf bound_ctrl:1
	v_fmac_f32_dpp v13, v27, v224 row_newbcast:4 row_mask:0xf bank_mask:0xf bound_ctrl:1
	v_fmac_f32_dpp v12, v27, v224 row_newbcast:5 row_mask:0xf bank_mask:0xf bound_ctrl:1
	v_fmac_f32_dpp v11, v27, v224 row_newbcast:6 row_mask:0xf bank_mask:0xf bound_ctrl:1
	v_fmac_f32_dpp v10, v27, v224 row_newbcast:7 row_mask:0xf bank_mask:0xf bound_ctrl:1
	v_fmac_f32_dpp v9, v27, v224 row_newbcast:8 row_mask:0xf bank_mask:0xf bound_ctrl:1
	v_fmac_f32_dpp v8, v27, v224 row_newbcast:9 row_mask:0xf bank_mask:0xf bound_ctrl:1
	v_fmac_f32_dpp v7, v27, v224 row_newbcast:10 row_mask:0xf bank_mask:0xf bound_ctrl:1
	v_fmac_f32_dpp v6, v27, v224 row_newbcast:11 row_mask:0xf bank_mask:0xf bound_ctrl:1
	v_fmac_f32_dpp v5, v27, v224 row_newbcast:12 row_mask:0xf bank_mask:0xf bound_ctrl:1
	v_fmac_f32_dpp v4, v27, v224 row_newbcast:13 row_mask:0xf bank_mask:0xf bound_ctrl:1
	v_fmac_f32_dpp v3, v27, v224 row_newbcast:14 row_mask:0xf bank_mask:0xf bound_ctrl:1
	v_fmac_f32_dpp v2, v27, v224 row_newbcast:15 row_mask:0xf bank_mask:0xf bound_ctrl:1
	v_add_f32 v39, v39, v40
	s_nop 1
	v_mfma_f32_16x16x4_f32 v[232:235], v228, v39, 0
	ds_write_b64 v22, v[24:25] offset:59392
	v_fmac_f32_dpp v17, v28, v36 row_newbcast:0 row_mask:0xf bank_mask:0xf bound_ctrl:1
	v_fmac_f32_dpp v16, v28, v36 row_newbcast:1 row_mask:0xf bank_mask:0xf bound_ctrl:1
	v_fmac_f32_dpp v15, v28, v36 row_newbcast:2 row_mask:0xf bank_mask:0xf bound_ctrl:1
	v_fmac_f32_dpp v14, v28, v36 row_newbcast:3 row_mask:0xf bank_mask:0xf bound_ctrl:1
	v_fmac_f32_dpp v13, v28, v36 row_newbcast:4 row_mask:0xf bank_mask:0xf bound_ctrl:1
	v_fmac_f32_dpp v12, v28, v36 row_newbcast:5 row_mask:0xf bank_mask:0xf bound_ctrl:1
	v_fmac_f32_dpp v11, v28, v36 row_newbcast:6 row_mask:0xf bank_mask:0xf bound_ctrl:1
	v_fmac_f32_dpp v10, v28, v36 row_newbcast:7 row_mask:0xf bank_mask:0xf bound_ctrl:1
	v_fmac_f32_dpp v9, v28, v36 row_newbcast:8 row_mask:0xf bank_mask:0xf bound_ctrl:1
	v_fmac_f32_dpp v8, v28, v36 row_newbcast:9 row_mask:0xf bank_mask:0xf bound_ctrl:1
	v_fmac_f32_dpp v7, v28, v36 row_newbcast:10 row_mask:0xf bank_mask:0xf bound_ctrl:1
	v_fmac_f32_dpp v6, v28, v36 row_newbcast:11 row_mask:0xf bank_mask:0xf bound_ctrl:1
	v_fmac_f32_dpp v5, v28, v36 row_newbcast:12 row_mask:0xf bank_mask:0xf bound_ctrl:1
	v_fmac_f32_dpp v4, v28, v36 row_newbcast:13 row_mask:0xf bank_mask:0xf bound_ctrl:1
	v_fmac_f32_dpp v3, v28, v36 row_newbcast:14 row_mask:0xf bank_mask:0xf bound_ctrl:1
	v_fmac_f32_dpp v2, v28, v36 row_newbcast:15 row_mask:0xf bank_mask:0xf bound_ctrl:1
	v_mul_f32_dpp v24, v29, v17 row_newbcast:0 row_mask:0xf bank_mask:0xf bound_ctrl:1
	v_mul_f32_dpp v25, v29, v16 row_newbcast:1 row_mask:0xf bank_mask:0xf bound_ctrl:1
	v_fmac_f32_dpp v24, v29, v15 row_newbcast:2 row_mask:0xf bank_mask:0xf bound_ctrl:1
	v_fmac_f32_dpp v25, v29, v14 row_newbcast:3 row_mask:0xf bank_mask:0xf bound_ctrl:1
	v_fmac_f32_dpp v24, v29, v13 row_newbcast:4 row_mask:0xf bank_mask:0xf bound_ctrl:1
	v_fmac_f32_dpp v25, v29, v12 row_newbcast:5 row_mask:0xf bank_mask:0xf bound_ctrl:1
	v_fmac_f32_dpp v24, v29, v11 row_newbcast:6 row_mask:0xf bank_mask:0xf bound_ctrl:1
	v_fmac_f32_dpp v25, v29, v10 row_newbcast:7 row_mask:0xf bank_mask:0xf bound_ctrl:1
	v_fmac_f32_dpp v24, v29, v9 row_newbcast:8 row_mask:0xf bank_mask:0xf bound_ctrl:1
	v_fmac_f32_dpp v25, v29, v8 row_newbcast:9 row_mask:0xf bank_mask:0xf bound_ctrl:1
	v_fmac_f32_dpp v24, v29, v7 row_newbcast:10 row_mask:0xf bank_mask:0xf bound_ctrl:1
	v_fmac_f32_dpp v25, v29, v6 row_newbcast:11 row_mask:0xf bank_mask:0xf bound_ctrl:1
	v_fmac_f32_dpp v24, v29, v5 row_newbcast:12 row_mask:0xf bank_mask:0xf bound_ctrl:1
	v_fmac_f32_dpp v25, v29, v4 row_newbcast:13 row_mask:0xf bank_mask:0xf bound_ctrl:1
	v_fmac_f32_dpp v24, v29, v3 row_newbcast:14 row_mask:0xf bank_mask:0xf bound_ctrl:1
	v_fmac_f32_dpp v25, v29, v2 row_newbcast:15 row_mask:0xf bank_mask:0xf bound_ctrl:1
	s_waitcnt lgkmcnt(0)
	ds_read_b32 v34, v19 offset:22528
	ds_read2st64_b32 v[26:27], v21 offset0:24 offset1:40
	ds_read2st64_b32 v[28:29], v21 offset0:56 offset1:72
	v_mul_f32_dpp v35, v30, v17 row_newbcast:0 row_mask:0xf bank_mask:0xf bound_ctrl:1
	v_mul_f32_dpp v40, v30, v16 row_newbcast:1 row_mask:0xf bank_mask:0xf bound_ctrl:1
	v_fmac_f32_dpp v35, v30, v15 row_newbcast:2 row_mask:0xf bank_mask:0xf bound_ctrl:1
	v_fmac_f32_dpp v40, v30, v14 row_newbcast:3 row_mask:0xf bank_mask:0xf bound_ctrl:1
	v_fmac_f32_dpp v232, v229, v224 row_newbcast:6 row_mask:0xf bank_mask:0xf bound_ctrl:1
	v_fmac_f32_dpp v35, v30, v13 row_newbcast:4 row_mask:0xf bank_mask:0xf bound_ctrl:1
	v_fmac_f32_dpp v40, v30, v12 row_newbcast:5 row_mask:0xf bank_mask:0xf bound_ctrl:1
	v_fmac_f32_dpp v35, v30, v11 row_newbcast:6 row_mask:0xf bank_mask:0xf bound_ctrl:1
	v_fmac_f32_dpp v40, v30, v10 row_newbcast:7 row_mask:0xf bank_mask:0xf bound_ctrl:1
	v_fmac_f32_dpp v232, v230, v36 row_newbcast:6 row_mask:0xf bank_mask:0xf bound_ctrl:1
	v_fmac_f32_dpp v35, v30, v9 row_newbcast:8 row_mask:0xf bank_mask:0xf bound_ctrl:1
	v_fmac_f32_dpp v40, v30, v8 row_newbcast:9 row_mask:0xf bank_mask:0xf bound_ctrl:1
	v_fmac_f32_dpp v35, v30, v7 row_newbcast:10 row_mask:0xf bank_mask:0xf bound_ctrl:1
	v_fmac_f32_dpp v40, v30, v6 row_newbcast:11 row_mask:0xf bank_mask:0xf bound_ctrl:1
	v_fmac_f32_dpp v35, v30, v5 row_newbcast:12 row_mask:0xf bank_mask:0xf bound_ctrl:1
	v_fmac_f32_dpp v40, v30, v4 row_newbcast:13 row_mask:0xf bank_mask:0xf bound_ctrl:1
	v_fmac_f32_dpp v35, v30, v3 row_newbcast:14 row_mask:0xf bank_mask:0xf bound_ctrl:1
	v_fmac_f32_dpp v40, v30, v2 row_newbcast:15 row_mask:0xf bank_mask:0xf bound_ctrl:1
	v_fmac_f32_dpp v17, v31, v232 row_newbcast:0 row_mask:0xf bank_mask:0xf bound_ctrl:1
	v_fmac_f32_dpp v16, v31, v232 row_newbcast:1 row_mask:0xf bank_mask:0xf bound_ctrl:1
	v_fmac_f32_dpp v15, v31, v232 row_newbcast:2 row_mask:0xf bank_mask:0xf bound_ctrl:1
	v_fmac_f32_dpp v14, v31, v232 row_newbcast:3 row_mask:0xf bank_mask:0xf bound_ctrl:1
	v_fmac_f32_dpp v13, v31, v232 row_newbcast:4 row_mask:0xf bank_mask:0xf bound_ctrl:1
	v_fmac_f32_dpp v12, v31, v232 row_newbcast:5 row_mask:0xf bank_mask:0xf bound_ctrl:1
	v_fmac_f32_dpp v11, v31, v232 row_newbcast:6 row_mask:0xf bank_mask:0xf bound_ctrl:1
	v_fmac_f32_dpp v10, v31, v232 row_newbcast:7 row_mask:0xf bank_mask:0xf bound_ctrl:1
	v_fmac_f32_dpp v9, v31, v232 row_newbcast:8 row_mask:0xf bank_mask:0xf bound_ctrl:1
	v_fmac_f32_dpp v8, v31, v232 row_newbcast:9 row_mask:0xf bank_mask:0xf bound_ctrl:1
	v_fmac_f32_dpp v7, v31, v232 row_newbcast:10 row_mask:0xf bank_mask:0xf bound_ctrl:1
	v_fmac_f32_dpp v6, v31, v232 row_newbcast:11 row_mask:0xf bank_mask:0xf bound_ctrl:1
	v_fmac_f32_dpp v5, v31, v232 row_newbcast:12 row_mask:0xf bank_mask:0xf bound_ctrl:1
	v_fmac_f32_dpp v4, v31, v232 row_newbcast:13 row_mask:0xf bank_mask:0xf bound_ctrl:1
	v_fmac_f32_dpp v3, v31, v232 row_newbcast:14 row_mask:0xf bank_mask:0xf bound_ctrl:1
	v_fmac_f32_dpp v2, v31, v232 row_newbcast:15 row_mask:0xf bank_mask:0xf bound_ctrl:1
	v_add_f32 v35, v35, v40
	s_nop 1
	v_mfma_f32_16x16x4_f32 v[224:227], v228, v35, 0
	ds_write_b64 v22, v[24:25] offset:61440
	v_fmac_f32_dpp v17, v32, v38 row_newbcast:0 row_mask:0xf bank_mask:0xf bound_ctrl:1
	v_fmac_f32_dpp v16, v32, v38 row_newbcast:1 row_mask:0xf bank_mask:0xf bound_ctrl:1
	v_fmac_f32_dpp v15, v32, v38 row_newbcast:2 row_mask:0xf bank_mask:0xf bound_ctrl:1
	v_fmac_f32_dpp v14, v32, v38 row_newbcast:3 row_mask:0xf bank_mask:0xf bound_ctrl:1
	v_fmac_f32_dpp v13, v32, v38 row_newbcast:4 row_mask:0xf bank_mask:0xf bound_ctrl:1
	v_fmac_f32_dpp v12, v32, v38 row_newbcast:5 row_mask:0xf bank_mask:0xf bound_ctrl:1
	v_fmac_f32_dpp v11, v32, v38 row_newbcast:6 row_mask:0xf bank_mask:0xf bound_ctrl:1
	v_fmac_f32_dpp v10, v32, v38 row_newbcast:7 row_mask:0xf bank_mask:0xf bound_ctrl:1
	v_fmac_f32_dpp v9, v32, v38 row_newbcast:8 row_mask:0xf bank_mask:0xf bound_ctrl:1
	v_fmac_f32_dpp v8, v32, v38 row_newbcast:9 row_mask:0xf bank_mask:0xf bound_ctrl:1
	v_fmac_f32_dpp v7, v32, v38 row_newbcast:10 row_mask:0xf bank_mask:0xf bound_ctrl:1
	v_fmac_f32_dpp v6, v32, v38 row_newbcast:11 row_mask:0xf bank_mask:0xf bound_ctrl:1
	v_fmac_f32_dpp v5, v32, v38 row_newbcast:12 row_mask:0xf bank_mask:0xf bound_ctrl:1
	v_fmac_f32_dpp v4, v32, v38 row_newbcast:13 row_mask:0xf bank_mask:0xf bound_ctrl:1
	v_fmac_f32_dpp v3, v32, v38 row_newbcast:14 row_mask:0xf bank_mask:0xf bound_ctrl:1
	v_fmac_f32_dpp v2, v32, v38 row_newbcast:15 row_mask:0xf bank_mask:0xf bound_ctrl:1
	v_mul_f32_dpp v24, v33, v17 row_newbcast:0 row_mask:0xf bank_mask:0xf bound_ctrl:1
	v_mul_f32_dpp v25, v33, v16 row_newbcast:1 row_mask:0xf bank_mask:0xf bound_ctrl:1
	v_fmac_f32_dpp v24, v33, v15 row_newbcast:2 row_mask:0xf bank_mask:0xf bound_ctrl:1
	v_fmac_f32_dpp v25, v33, v14 row_newbcast:3 row_mask:0xf bank_mask:0xf bound_ctrl:1
	v_fmac_f32_dpp v24, v33, v13 row_newbcast:4 row_mask:0xf bank_mask:0xf bound_ctrl:1
	v_fmac_f32_dpp v25, v33, v12 row_newbcast:5 row_mask:0xf bank_mask:0xf bound_ctrl:1
	v_fmac_f32_dpp v24, v33, v11 row_newbcast:6 row_mask:0xf bank_mask:0xf bound_ctrl:1
	v_fmac_f32_dpp v25, v33, v10 row_newbcast:7 row_mask:0xf bank_mask:0xf bound_ctrl:1
	v_fmac_f32_dpp v24, v33, v9 row_newbcast:8 row_mask:0xf bank_mask:0xf bound_ctrl:1
	v_fmac_f32_dpp v25, v33, v8 row_newbcast:9 row_mask:0xf bank_mask:0xf bound_ctrl:1
	v_fmac_f32_dpp v24, v33, v7 row_newbcast:10 row_mask:0xf bank_mask:0xf bound_ctrl:1
	v_fmac_f32_dpp v25, v33, v6 row_newbcast:11 row_mask:0xf bank_mask:0xf bound_ctrl:1
	v_fmac_f32_dpp v24, v33, v5 row_newbcast:12 row_mask:0xf bank_mask:0xf bound_ctrl:1
	v_fmac_f32_dpp v25, v33, v4 row_newbcast:13 row_mask:0xf bank_mask:0xf bound_ctrl:1
	v_fmac_f32_dpp v24, v33, v3 row_newbcast:14 row_mask:0xf bank_mask:0xf bound_ctrl:1
	v_fmac_f32_dpp v25, v33, v2 row_newbcast:15 row_mask:0xf bank_mask:0xf bound_ctrl:1
	s_waitcnt lgkmcnt(0)
	ds_read_b32 v36, v19 offset:22784
	ds_read2st64_b32 v[30:31], v21 offset0:25 offset1:41
	ds_read2st64_b32 v[32:33], v21 offset0:57 offset1:73
	v_mul_f32_dpp v37, v26, v17 row_newbcast:0 row_mask:0xf bank_mask:0xf bound_ctrl:1
	v_mul_f32_dpp v40, v26, v16 row_newbcast:1 row_mask:0xf bank_mask:0xf bound_ctrl:1
	v_fmac_f32_dpp v37, v26, v15 row_newbcast:2 row_mask:0xf bank_mask:0xf bound_ctrl:1
	v_fmac_f32_dpp v40, v26, v14 row_newbcast:3 row_mask:0xf bank_mask:0xf bound_ctrl:1
	v_fmac_f32_dpp v224, v229, v232 row_newbcast:7 row_mask:0xf bank_mask:0xf bound_ctrl:1
	v_fmac_f32_dpp v37, v26, v13 row_newbcast:4 row_mask:0xf bank_mask:0xf bound_ctrl:1
	v_fmac_f32_dpp v40, v26, v12 row_newbcast:5 row_mask:0xf bank_mask:0xf bound_ctrl:1
	v_fmac_f32_dpp v37, v26, v11 row_newbcast:6 row_mask:0xf bank_mask:0xf bound_ctrl:1
	v_fmac_f32_dpp v40, v26, v10 row_newbcast:7 row_mask:0xf bank_mask:0xf bound_ctrl:1
	v_fmac_f32_dpp v224, v230, v38 row_newbcast:7 row_mask:0xf bank_mask:0xf bound_ctrl:1
	v_fmac_f32_dpp v37, v26, v9 row_newbcast:8 row_mask:0xf bank_mask:0xf bound_ctrl:1
	v_fmac_f32_dpp v40, v26, v8 row_newbcast:9 row_mask:0xf bank_mask:0xf bound_ctrl:1
	v_fmac_f32_dpp v37, v26, v7 row_newbcast:10 row_mask:0xf bank_mask:0xf bound_ctrl:1
	v_fmac_f32_dpp v40, v26, v6 row_newbcast:11 row_mask:0xf bank_mask:0xf bound_ctrl:1
	v_fmac_f32_dpp v37, v26, v5 row_newbcast:12 row_mask:0xf bank_mask:0xf bound_ctrl:1
	v_fmac_f32_dpp v40, v26, v4 row_newbcast:13 row_mask:0xf bank_mask:0xf bound_ctrl:1
	v_fmac_f32_dpp v37, v26, v3 row_newbcast:14 row_mask:0xf bank_mask:0xf bound_ctrl:1
	v_fmac_f32_dpp v40, v26, v2 row_newbcast:15 row_mask:0xf bank_mask:0xf bound_ctrl:1
	v_fmac_f32_dpp v17, v27, v224 row_newbcast:0 row_mask:0xf bank_mask:0xf bound_ctrl:1
	v_fmac_f32_dpp v16, v27, v224 row_newbcast:1 row_mask:0xf bank_mask:0xf bound_ctrl:1
	v_fmac_f32_dpp v15, v27, v224 row_newbcast:2 row_mask:0xf bank_mask:0xf bound_ctrl:1
	v_fmac_f32_dpp v14, v27, v224 row_newbcast:3 row_mask:0xf bank_mask:0xf bound_ctrl:1
	v_fmac_f32_dpp v13, v27, v224 row_newbcast:4 row_mask:0xf bank_mask:0xf bound_ctrl:1
	v_fmac_f32_dpp v12, v27, v224 row_newbcast:5 row_mask:0xf bank_mask:0xf bound_ctrl:1
	v_fmac_f32_dpp v11, v27, v224 row_newbcast:6 row_mask:0xf bank_mask:0xf bound_ctrl:1
	v_fmac_f32_dpp v10, v27, v224 row_newbcast:7 row_mask:0xf bank_mask:0xf bound_ctrl:1
	v_fmac_f32_dpp v9, v27, v224 row_newbcast:8 row_mask:0xf bank_mask:0xf bound_ctrl:1
	v_fmac_f32_dpp v8, v27, v224 row_newbcast:9 row_mask:0xf bank_mask:0xf bound_ctrl:1
	v_fmac_f32_dpp v7, v27, v224 row_newbcast:10 row_mask:0xf bank_mask:0xf bound_ctrl:1
	v_fmac_f32_dpp v6, v27, v224 row_newbcast:11 row_mask:0xf bank_mask:0xf bound_ctrl:1
	v_fmac_f32_dpp v5, v27, v224 row_newbcast:12 row_mask:0xf bank_mask:0xf bound_ctrl:1
	v_fmac_f32_dpp v4, v27, v224 row_newbcast:13 row_mask:0xf bank_mask:0xf bound_ctrl:1
	v_fmac_f32_dpp v3, v27, v224 row_newbcast:14 row_mask:0xf bank_mask:0xf bound_ctrl:1
	v_fmac_f32_dpp v2, v27, v224 row_newbcast:15 row_mask:0xf bank_mask:0xf bound_ctrl:1
	v_add_f32 v37, v37, v40
	s_nop 1
	v_mfma_f32_16x16x4_f32 v[232:235], v228, v37, 0
	ds_write_b64 v22, v[24:25] offset:63488
	v_fmac_f32_dpp v17, v28, v34 row_newbcast:0 row_mask:0xf bank_mask:0xf bound_ctrl:1
	v_fmac_f32_dpp v16, v28, v34 row_newbcast:1 row_mask:0xf bank_mask:0xf bound_ctrl:1
	v_fmac_f32_dpp v15, v28, v34 row_newbcast:2 row_mask:0xf bank_mask:0xf bound_ctrl:1
	v_fmac_f32_dpp v14, v28, v34 row_newbcast:3 row_mask:0xf bank_mask:0xf bound_ctrl:1
	v_fmac_f32_dpp v13, v28, v34 row_newbcast:4 row_mask:0xf bank_mask:0xf bound_ctrl:1
	v_fmac_f32_dpp v12, v28, v34 row_newbcast:5 row_mask:0xf bank_mask:0xf bound_ctrl:1
	v_fmac_f32_dpp v11, v28, v34 row_newbcast:6 row_mask:0xf bank_mask:0xf bound_ctrl:1
	v_fmac_f32_dpp v10, v28, v34 row_newbcast:7 row_mask:0xf bank_mask:0xf bound_ctrl:1
	v_fmac_f32_dpp v9, v28, v34 row_newbcast:8 row_mask:0xf bank_mask:0xf bound_ctrl:1
	v_fmac_f32_dpp v8, v28, v34 row_newbcast:9 row_mask:0xf bank_mask:0xf bound_ctrl:1
	v_fmac_f32_dpp v7, v28, v34 row_newbcast:10 row_mask:0xf bank_mask:0xf bound_ctrl:1
	v_fmac_f32_dpp v6, v28, v34 row_newbcast:11 row_mask:0xf bank_mask:0xf bound_ctrl:1
	v_fmac_f32_dpp v5, v28, v34 row_newbcast:12 row_mask:0xf bank_mask:0xf bound_ctrl:1
	v_fmac_f32_dpp v4, v28, v34 row_newbcast:13 row_mask:0xf bank_mask:0xf bound_ctrl:1
	v_fmac_f32_dpp v3, v28, v34 row_newbcast:14 row_mask:0xf bank_mask:0xf bound_ctrl:1
	v_fmac_f32_dpp v2, v28, v34 row_newbcast:15 row_mask:0xf bank_mask:0xf bound_ctrl:1
	v_mul_f32_dpp v22, v29, v17 row_newbcast:0 row_mask:0xf bank_mask:0xf bound_ctrl:1
	v_mul_f32_dpp v23, v29, v16 row_newbcast:1 row_mask:0xf bank_mask:0xf bound_ctrl:1
	v_fmac_f32_dpp v22, v29, v15 row_newbcast:2 row_mask:0xf bank_mask:0xf bound_ctrl:1
	v_fmac_f32_dpp v23, v29, v14 row_newbcast:3 row_mask:0xf bank_mask:0xf bound_ctrl:1
	v_fmac_f32_dpp v22, v29, v13 row_newbcast:4 row_mask:0xf bank_mask:0xf bound_ctrl:1
	v_fmac_f32_dpp v23, v29, v12 row_newbcast:5 row_mask:0xf bank_mask:0xf bound_ctrl:1
	v_fmac_f32_dpp v22, v29, v11 row_newbcast:6 row_mask:0xf bank_mask:0xf bound_ctrl:1
	v_fmac_f32_dpp v23, v29, v10 row_newbcast:7 row_mask:0xf bank_mask:0xf bound_ctrl:1
	v_fmac_f32_dpp v22, v29, v9 row_newbcast:8 row_mask:0xf bank_mask:0xf bound_ctrl:1
	v_fmac_f32_dpp v23, v29, v8 row_newbcast:9 row_mask:0xf bank_mask:0xf bound_ctrl:1
	v_fmac_f32_dpp v22, v29, v7 row_newbcast:10 row_mask:0xf bank_mask:0xf bound_ctrl:1
	v_fmac_f32_dpp v23, v29, v6 row_newbcast:11 row_mask:0xf bank_mask:0xf bound_ctrl:1
	v_fmac_f32_dpp v22, v29, v5 row_newbcast:12 row_mask:0xf bank_mask:0xf bound_ctrl:1
	v_fmac_f32_dpp v23, v29, v4 row_newbcast:13 row_mask:0xf bank_mask:0xf bound_ctrl:1
	v_fmac_f32_dpp v22, v29, v3 row_newbcast:14 row_mask:0xf bank_mask:0xf bound_ctrl:1
	v_fmac_f32_dpp v23, v29, v2 row_newbcast:15 row_mask:0xf bank_mask:0xf bound_ctrl:1
	s_waitcnt lgkmcnt(0)
	ds_read_b32 v38, v19 offset:23040
	ds_read2st64_b32 v[24:25], v21 offset0:26 offset1:42
	ds_read2st64_b32 v[26:27], v21 offset0:58 offset1:74
	v_mul_f32_dpp v39, v30, v17 row_newbcast:0 row_mask:0xf bank_mask:0xf bound_ctrl:1
	v_mul_f32_dpp v29, v30, v16 row_newbcast:1 row_mask:0xf bank_mask:0xf bound_ctrl:1
	v_fmac_f32_dpp v39, v30, v15 row_newbcast:2 row_mask:0xf bank_mask:0xf bound_ctrl:1
	v_fmac_f32_dpp v29, v30, v14 row_newbcast:3 row_mask:0xf bank_mask:0xf bound_ctrl:1
	v_fmac_f32_dpp v232, v229, v224 row_newbcast:8 row_mask:0xf bank_mask:0xf bound_ctrl:1
	v_fmac_f32_dpp v39, v30, v13 row_newbcast:4 row_mask:0xf bank_mask:0xf bound_ctrl:1
	v_fmac_f32_dpp v29, v30, v12 row_newbcast:5 row_mask:0xf bank_mask:0xf bound_ctrl:1
	v_fmac_f32_dpp v39, v30, v11 row_newbcast:6 row_mask:0xf bank_mask:0xf bound_ctrl:1
	v_fmac_f32_dpp v29, v30, v10 row_newbcast:7 row_mask:0xf bank_mask:0xf bound_ctrl:1
	v_fmac_f32_dpp v232, v230, v34 row_newbcast:8 row_mask:0xf bank_mask:0xf bound_ctrl:1
	v_fmac_f32_dpp v39, v30, v9 row_newbcast:8 row_mask:0xf bank_mask:0xf bound_ctrl:1
	v_fmac_f32_dpp v29, v30, v8 row_newbcast:9 row_mask:0xf bank_mask:0xf bound_ctrl:1
	v_fmac_f32_dpp v39, v30, v7 row_newbcast:10 row_mask:0xf bank_mask:0xf bound_ctrl:1
	v_fmac_f32_dpp v29, v30, v6 row_newbcast:11 row_mask:0xf bank_mask:0xf bound_ctrl:1
	v_fmac_f32_dpp v39, v30, v5 row_newbcast:12 row_mask:0xf bank_mask:0xf bound_ctrl:1
	v_fmac_f32_dpp v29, v30, v4 row_newbcast:13 row_mask:0xf bank_mask:0xf bound_ctrl:1
	v_fmac_f32_dpp v39, v30, v3 row_newbcast:14 row_mask:0xf bank_mask:0xf bound_ctrl:1
	v_fmac_f32_dpp v29, v30, v2 row_newbcast:15 row_mask:0xf bank_mask:0xf bound_ctrl:1
	v_fmac_f32_dpp v17, v31, v232 row_newbcast:0 row_mask:0xf bank_mask:0xf bound_ctrl:1
	v_fmac_f32_dpp v16, v31, v232 row_newbcast:1 row_mask:0xf bank_mask:0xf bound_ctrl:1
	v_fmac_f32_dpp v15, v31, v232 row_newbcast:2 row_mask:0xf bank_mask:0xf bound_ctrl:1
	v_fmac_f32_dpp v14, v31, v232 row_newbcast:3 row_mask:0xf bank_mask:0xf bound_ctrl:1
	v_fmac_f32_dpp v13, v31, v232 row_newbcast:4 row_mask:0xf bank_mask:0xf bound_ctrl:1
	v_fmac_f32_dpp v12, v31, v232 row_newbcast:5 row_mask:0xf bank_mask:0xf bound_ctrl:1
	v_fmac_f32_dpp v11, v31, v232 row_newbcast:6 row_mask:0xf bank_mask:0xf bound_ctrl:1
	v_fmac_f32_dpp v10, v31, v232 row_newbcast:7 row_mask:0xf bank_mask:0xf bound_ctrl:1
	v_fmac_f32_dpp v9, v31, v232 row_newbcast:8 row_mask:0xf bank_mask:0xf bound_ctrl:1
	v_fmac_f32_dpp v8, v31, v232 row_newbcast:9 row_mask:0xf bank_mask:0xf bound_ctrl:1
	v_fmac_f32_dpp v7, v31, v232 row_newbcast:10 row_mask:0xf bank_mask:0xf bound_ctrl:1
	v_fmac_f32_dpp v6, v31, v232 row_newbcast:11 row_mask:0xf bank_mask:0xf bound_ctrl:1
	v_fmac_f32_dpp v5, v31, v232 row_newbcast:12 row_mask:0xf bank_mask:0xf bound_ctrl:1
	v_fmac_f32_dpp v4, v31, v232 row_newbcast:13 row_mask:0xf bank_mask:0xf bound_ctrl:1
	v_fmac_f32_dpp v3, v31, v232 row_newbcast:14 row_mask:0xf bank_mask:0xf bound_ctrl:1
	v_fmac_f32_dpp v2, v31, v232 row_newbcast:15 row_mask:0xf bank_mask:0xf bound_ctrl:1
	v_add_f32 v39, v39, v29
	s_nop 1
	v_mfma_f32_16x16x4_f32 v[224:227], v228, v39, 0
	ds_write_b64 v20, v[22:23] offset:16384
	v_fmac_f32_dpp v17, v32, v36 row_newbcast:0 row_mask:0xf bank_mask:0xf bound_ctrl:1
	v_fmac_f32_dpp v16, v32, v36 row_newbcast:1 row_mask:0xf bank_mask:0xf bound_ctrl:1
	v_fmac_f32_dpp v15, v32, v36 row_newbcast:2 row_mask:0xf bank_mask:0xf bound_ctrl:1
	v_fmac_f32_dpp v14, v32, v36 row_newbcast:3 row_mask:0xf bank_mask:0xf bound_ctrl:1
	v_fmac_f32_dpp v13, v32, v36 row_newbcast:4 row_mask:0xf bank_mask:0xf bound_ctrl:1
	v_fmac_f32_dpp v12, v32, v36 row_newbcast:5 row_mask:0xf bank_mask:0xf bound_ctrl:1
	v_fmac_f32_dpp v11, v32, v36 row_newbcast:6 row_mask:0xf bank_mask:0xf bound_ctrl:1
	v_fmac_f32_dpp v10, v32, v36 row_newbcast:7 row_mask:0xf bank_mask:0xf bound_ctrl:1
	v_fmac_f32_dpp v9, v32, v36 row_newbcast:8 row_mask:0xf bank_mask:0xf bound_ctrl:1
	v_fmac_f32_dpp v8, v32, v36 row_newbcast:9 row_mask:0xf bank_mask:0xf bound_ctrl:1
	v_fmac_f32_dpp v7, v32, v36 row_newbcast:10 row_mask:0xf bank_mask:0xf bound_ctrl:1
	v_fmac_f32_dpp v6, v32, v36 row_newbcast:11 row_mask:0xf bank_mask:0xf bound_ctrl:1
	v_fmac_f32_dpp v5, v32, v36 row_newbcast:12 row_mask:0xf bank_mask:0xf bound_ctrl:1
	v_fmac_f32_dpp v4, v32, v36 row_newbcast:13 row_mask:0xf bank_mask:0xf bound_ctrl:1
	v_fmac_f32_dpp v3, v32, v36 row_newbcast:14 row_mask:0xf bank_mask:0xf bound_ctrl:1
	v_fmac_f32_dpp v2, v32, v36 row_newbcast:15 row_mask:0xf bank_mask:0xf bound_ctrl:1
	v_mul_f32_dpp v22, v33, v17 row_newbcast:0 row_mask:0xf bank_mask:0xf bound_ctrl:1
	v_mul_f32_dpp v23, v33, v16 row_newbcast:1 row_mask:0xf bank_mask:0xf bound_ctrl:1
	v_fmac_f32_dpp v22, v33, v15 row_newbcast:2 row_mask:0xf bank_mask:0xf bound_ctrl:1
	v_fmac_f32_dpp v23, v33, v14 row_newbcast:3 row_mask:0xf bank_mask:0xf bound_ctrl:1
	v_fmac_f32_dpp v22, v33, v13 row_newbcast:4 row_mask:0xf bank_mask:0xf bound_ctrl:1
	v_fmac_f32_dpp v23, v33, v12 row_newbcast:5 row_mask:0xf bank_mask:0xf bound_ctrl:1
	v_fmac_f32_dpp v22, v33, v11 row_newbcast:6 row_mask:0xf bank_mask:0xf bound_ctrl:1
	v_fmac_f32_dpp v23, v33, v10 row_newbcast:7 row_mask:0xf bank_mask:0xf bound_ctrl:1
	v_fmac_f32_dpp v22, v33, v9 row_newbcast:8 row_mask:0xf bank_mask:0xf bound_ctrl:1
	v_fmac_f32_dpp v23, v33, v8 row_newbcast:9 row_mask:0xf bank_mask:0xf bound_ctrl:1
	v_fmac_f32_dpp v22, v33, v7 row_newbcast:10 row_mask:0xf bank_mask:0xf bound_ctrl:1
	v_fmac_f32_dpp v23, v33, v6 row_newbcast:11 row_mask:0xf bank_mask:0xf bound_ctrl:1
	v_fmac_f32_dpp v22, v33, v5 row_newbcast:12 row_mask:0xf bank_mask:0xf bound_ctrl:1
	v_fmac_f32_dpp v23, v33, v4 row_newbcast:13 row_mask:0xf bank_mask:0xf bound_ctrl:1
	v_fmac_f32_dpp v22, v33, v3 row_newbcast:14 row_mask:0xf bank_mask:0xf bound_ctrl:1
	v_fmac_f32_dpp v23, v33, v2 row_newbcast:15 row_mask:0xf bank_mask:0xf bound_ctrl:1
	s_waitcnt lgkmcnt(0)
	ds_read_b32 v33, v19 offset:23296
	ds_read2st64_b32 v[28:29], v21 offset0:27 offset1:43
	ds_read2st64_b32 v[30:31], v21 offset0:59 offset1:75
	v_mul_f32_dpp v34, v24, v17 row_newbcast:0 row_mask:0xf bank_mask:0xf bound_ctrl:1
	v_mul_f32_dpp v35, v24, v16 row_newbcast:1 row_mask:0xf bank_mask:0xf bound_ctrl:1
	v_fmac_f32_dpp v34, v24, v15 row_newbcast:2 row_mask:0xf bank_mask:0xf bound_ctrl:1
	v_fmac_f32_dpp v35, v24, v14 row_newbcast:3 row_mask:0xf bank_mask:0xf bound_ctrl:1
	v_fmac_f32_dpp v224, v229, v232 row_newbcast:9 row_mask:0xf bank_mask:0xf bound_ctrl:1
	v_fmac_f32_dpp v34, v24, v13 row_newbcast:4 row_mask:0xf bank_mask:0xf bound_ctrl:1
	v_fmac_f32_dpp v35, v24, v12 row_newbcast:5 row_mask:0xf bank_mask:0xf bound_ctrl:1
	v_fmac_f32_dpp v34, v24, v11 row_newbcast:6 row_mask:0xf bank_mask:0xf bound_ctrl:1
	v_fmac_f32_dpp v35, v24, v10 row_newbcast:7 row_mask:0xf bank_mask:0xf bound_ctrl:1
	v_fmac_f32_dpp v224, v230, v36 row_newbcast:9 row_mask:0xf bank_mask:0xf bound_ctrl:1
	v_fmac_f32_dpp v34, v24, v9 row_newbcast:8 row_mask:0xf bank_mask:0xf bound_ctrl:1
	v_fmac_f32_dpp v35, v24, v8 row_newbcast:9 row_mask:0xf bank_mask:0xf bound_ctrl:1
	v_fmac_f32_dpp v34, v24, v7 row_newbcast:10 row_mask:0xf bank_mask:0xf bound_ctrl:1
	v_fmac_f32_dpp v35, v24, v6 row_newbcast:11 row_mask:0xf bank_mask:0xf bound_ctrl:1
	v_fmac_f32_dpp v34, v24, v5 row_newbcast:12 row_mask:0xf bank_mask:0xf bound_ctrl:1
	v_fmac_f32_dpp v35, v24, v4 row_newbcast:13 row_mask:0xf bank_mask:0xf bound_ctrl:1
	v_fmac_f32_dpp v34, v24, v3 row_newbcast:14 row_mask:0xf bank_mask:0xf bound_ctrl:1
	v_fmac_f32_dpp v35, v24, v2 row_newbcast:15 row_mask:0xf bank_mask:0xf bound_ctrl:1
	v_fmac_f32_dpp v17, v25, v224 row_newbcast:0 row_mask:0xf bank_mask:0xf bound_ctrl:1
	v_fmac_f32_dpp v16, v25, v224 row_newbcast:1 row_mask:0xf bank_mask:0xf bound_ctrl:1
	v_fmac_f32_dpp v15, v25, v224 row_newbcast:2 row_mask:0xf bank_mask:0xf bound_ctrl:1
	v_fmac_f32_dpp v14, v25, v224 row_newbcast:3 row_mask:0xf bank_mask:0xf bound_ctrl:1
	v_fmac_f32_dpp v13, v25, v224 row_newbcast:4 row_mask:0xf bank_mask:0xf bound_ctrl:1
	v_fmac_f32_dpp v12, v25, v224 row_newbcast:5 row_mask:0xf bank_mask:0xf bound_ctrl:1
	v_fmac_f32_dpp v11, v25, v224 row_newbcast:6 row_mask:0xf bank_mask:0xf bound_ctrl:1
	v_fmac_f32_dpp v10, v25, v224 row_newbcast:7 row_mask:0xf bank_mask:0xf bound_ctrl:1
	v_fmac_f32_dpp v9, v25, v224 row_newbcast:8 row_mask:0xf bank_mask:0xf bound_ctrl:1
	v_fmac_f32_dpp v8, v25, v224 row_newbcast:9 row_mask:0xf bank_mask:0xf bound_ctrl:1
	v_fmac_f32_dpp v7, v25, v224 row_newbcast:10 row_mask:0xf bank_mask:0xf bound_ctrl:1
	v_fmac_f32_dpp v6, v25, v224 row_newbcast:11 row_mask:0xf bank_mask:0xf bound_ctrl:1
	v_fmac_f32_dpp v5, v25, v224 row_newbcast:12 row_mask:0xf bank_mask:0xf bound_ctrl:1
	v_fmac_f32_dpp v4, v25, v224 row_newbcast:13 row_mask:0xf bank_mask:0xf bound_ctrl:1
	v_fmac_f32_dpp v3, v25, v224 row_newbcast:14 row_mask:0xf bank_mask:0xf bound_ctrl:1
	v_fmac_f32_dpp v2, v25, v224 row_newbcast:15 row_mask:0xf bank_mask:0xf bound_ctrl:1
	v_add_f32 v34, v34, v35
	s_nop 1
	v_mfma_f32_16x16x4_f32 v[232:235], v228, v34, 0
	ds_write_b64 v20, v[22:23] offset:18432
	v_fmac_f32_dpp v17, v26, v38 row_newbcast:0 row_mask:0xf bank_mask:0xf bound_ctrl:1
	v_fmac_f32_dpp v16, v26, v38 row_newbcast:1 row_mask:0xf bank_mask:0xf bound_ctrl:1
	v_fmac_f32_dpp v15, v26, v38 row_newbcast:2 row_mask:0xf bank_mask:0xf bound_ctrl:1
	v_fmac_f32_dpp v14, v26, v38 row_newbcast:3 row_mask:0xf bank_mask:0xf bound_ctrl:1
	v_fmac_f32_dpp v13, v26, v38 row_newbcast:4 row_mask:0xf bank_mask:0xf bound_ctrl:1
	v_fmac_f32_dpp v12, v26, v38 row_newbcast:5 row_mask:0xf bank_mask:0xf bound_ctrl:1
	v_fmac_f32_dpp v11, v26, v38 row_newbcast:6 row_mask:0xf bank_mask:0xf bound_ctrl:1
	v_fmac_f32_dpp v10, v26, v38 row_newbcast:7 row_mask:0xf bank_mask:0xf bound_ctrl:1
	v_fmac_f32_dpp v9, v26, v38 row_newbcast:8 row_mask:0xf bank_mask:0xf bound_ctrl:1
	v_fmac_f32_dpp v8, v26, v38 row_newbcast:9 row_mask:0xf bank_mask:0xf bound_ctrl:1
	v_fmac_f32_dpp v7, v26, v38 row_newbcast:10 row_mask:0xf bank_mask:0xf bound_ctrl:1
	v_fmac_f32_dpp v6, v26, v38 row_newbcast:11 row_mask:0xf bank_mask:0xf bound_ctrl:1
	v_fmac_f32_dpp v5, v26, v38 row_newbcast:12 row_mask:0xf bank_mask:0xf bound_ctrl:1
	v_fmac_f32_dpp v4, v26, v38 row_newbcast:13 row_mask:0xf bank_mask:0xf bound_ctrl:1
	v_fmac_f32_dpp v3, v26, v38 row_newbcast:14 row_mask:0xf bank_mask:0xf bound_ctrl:1
	v_fmac_f32_dpp v2, v26, v38 row_newbcast:15 row_mask:0xf bank_mask:0xf bound_ctrl:1
	v_mul_f32_dpp v22, v27, v17 row_newbcast:0 row_mask:0xf bank_mask:0xf bound_ctrl:1
	v_mul_f32_dpp v23, v27, v16 row_newbcast:1 row_mask:0xf bank_mask:0xf bound_ctrl:1
	v_fmac_f32_dpp v22, v27, v15 row_newbcast:2 row_mask:0xf bank_mask:0xf bound_ctrl:1
	v_fmac_f32_dpp v23, v27, v14 row_newbcast:3 row_mask:0xf bank_mask:0xf bound_ctrl:1
	v_fmac_f32_dpp v22, v27, v13 row_newbcast:4 row_mask:0xf bank_mask:0xf bound_ctrl:1
	v_fmac_f32_dpp v23, v27, v12 row_newbcast:5 row_mask:0xf bank_mask:0xf bound_ctrl:1
	v_fmac_f32_dpp v22, v27, v11 row_newbcast:6 row_mask:0xf bank_mask:0xf bound_ctrl:1
	v_fmac_f32_dpp v23, v27, v10 row_newbcast:7 row_mask:0xf bank_mask:0xf bound_ctrl:1
	v_fmac_f32_dpp v22, v27, v9 row_newbcast:8 row_mask:0xf bank_mask:0xf bound_ctrl:1
	v_fmac_f32_dpp v23, v27, v8 row_newbcast:9 row_mask:0xf bank_mask:0xf bound_ctrl:1
	v_fmac_f32_dpp v22, v27, v7 row_newbcast:10 row_mask:0xf bank_mask:0xf bound_ctrl:1
	v_fmac_f32_dpp v23, v27, v6 row_newbcast:11 row_mask:0xf bank_mask:0xf bound_ctrl:1
	v_fmac_f32_dpp v22, v27, v5 row_newbcast:12 row_mask:0xf bank_mask:0xf bound_ctrl:1
	v_fmac_f32_dpp v23, v27, v4 row_newbcast:13 row_mask:0xf bank_mask:0xf bound_ctrl:1
	v_fmac_f32_dpp v22, v27, v3 row_newbcast:14 row_mask:0xf bank_mask:0xf bound_ctrl:1
	v_fmac_f32_dpp v23, v27, v2 row_newbcast:15 row_mask:0xf bank_mask:0xf bound_ctrl:1
	s_waitcnt lgkmcnt(0)
	ds_read_b32 v35, v19 offset:23552
	ds_read2st64_b32 v[24:25], v21 offset0:28 offset1:44
	ds_read2st64_b32 v[26:27], v21 offset0:60 offset1:76
	v_mul_f32_dpp v36, v28, v17 row_newbcast:0 row_mask:0xf bank_mask:0xf bound_ctrl:1
	v_mul_f32_dpp v37, v28, v16 row_newbcast:1 row_mask:0xf bank_mask:0xf bound_ctrl:1
	v_fmac_f32_dpp v36, v28, v15 row_newbcast:2 row_mask:0xf bank_mask:0xf bound_ctrl:1
	v_fmac_f32_dpp v37, v28, v14 row_newbcast:3 row_mask:0xf bank_mask:0xf bound_ctrl:1
	v_fmac_f32_dpp v232, v229, v224 row_newbcast:10 row_mask:0xf bank_mask:0xf bound_ctrl:1
	v_fmac_f32_dpp v36, v28, v13 row_newbcast:4 row_mask:0xf bank_mask:0xf bound_ctrl:1
	v_fmac_f32_dpp v37, v28, v12 row_newbcast:5 row_mask:0xf bank_mask:0xf bound_ctrl:1
	v_fmac_f32_dpp v36, v28, v11 row_newbcast:6 row_mask:0xf bank_mask:0xf bound_ctrl:1
	v_fmac_f32_dpp v37, v28, v10 row_newbcast:7 row_mask:0xf bank_mask:0xf bound_ctrl:1
	v_fmac_f32_dpp v232, v230, v38 row_newbcast:10 row_mask:0xf bank_mask:0xf bound_ctrl:1
	v_fmac_f32_dpp v36, v28, v9 row_newbcast:8 row_mask:0xf bank_mask:0xf bound_ctrl:1
	v_fmac_f32_dpp v37, v28, v8 row_newbcast:9 row_mask:0xf bank_mask:0xf bound_ctrl:1
	v_fmac_f32_dpp v36, v28, v7 row_newbcast:10 row_mask:0xf bank_mask:0xf bound_ctrl:1
	v_fmac_f32_dpp v37, v28, v6 row_newbcast:11 row_mask:0xf bank_mask:0xf bound_ctrl:1
	v_fmac_f32_dpp v36, v28, v5 row_newbcast:12 row_mask:0xf bank_mask:0xf bound_ctrl:1
	v_fmac_f32_dpp v37, v28, v4 row_newbcast:13 row_mask:0xf bank_mask:0xf bound_ctrl:1
	v_fmac_f32_dpp v36, v28, v3 row_newbcast:14 row_mask:0xf bank_mask:0xf bound_ctrl:1
	v_fmac_f32_dpp v37, v28, v2 row_newbcast:15 row_mask:0xf bank_mask:0xf bound_ctrl:1
	v_fmac_f32_dpp v17, v29, v232 row_newbcast:0 row_mask:0xf bank_mask:0xf bound_ctrl:1
	v_fmac_f32_dpp v16, v29, v232 row_newbcast:1 row_mask:0xf bank_mask:0xf bound_ctrl:1
	v_fmac_f32_dpp v15, v29, v232 row_newbcast:2 row_mask:0xf bank_mask:0xf bound_ctrl:1
	v_fmac_f32_dpp v14, v29, v232 row_newbcast:3 row_mask:0xf bank_mask:0xf bound_ctrl:1
	v_fmac_f32_dpp v13, v29, v232 row_newbcast:4 row_mask:0xf bank_mask:0xf bound_ctrl:1
	v_fmac_f32_dpp v12, v29, v232 row_newbcast:5 row_mask:0xf bank_mask:0xf bound_ctrl:1
	v_fmac_f32_dpp v11, v29, v232 row_newbcast:6 row_mask:0xf bank_mask:0xf bound_ctrl:1
	v_fmac_f32_dpp v10, v29, v232 row_newbcast:7 row_mask:0xf bank_mask:0xf bound_ctrl:1
	v_fmac_f32_dpp v9, v29, v232 row_newbcast:8 row_mask:0xf bank_mask:0xf bound_ctrl:1
	v_fmac_f32_dpp v8, v29, v232 row_newbcast:9 row_mask:0xf bank_mask:0xf bound_ctrl:1
	v_fmac_f32_dpp v7, v29, v232 row_newbcast:10 row_mask:0xf bank_mask:0xf bound_ctrl:1
	v_fmac_f32_dpp v6, v29, v232 row_newbcast:11 row_mask:0xf bank_mask:0xf bound_ctrl:1
	v_fmac_f32_dpp v5, v29, v232 row_newbcast:12 row_mask:0xf bank_mask:0xf bound_ctrl:1
	v_fmac_f32_dpp v4, v29, v232 row_newbcast:13 row_mask:0xf bank_mask:0xf bound_ctrl:1
	v_fmac_f32_dpp v3, v29, v232 row_newbcast:14 row_mask:0xf bank_mask:0xf bound_ctrl:1
	v_fmac_f32_dpp v2, v29, v232 row_newbcast:15 row_mask:0xf bank_mask:0xf bound_ctrl:1
	v_add_f32 v36, v36, v37
	s_nop 1
	v_mfma_f32_16x16x4_f32 v[224:227], v228, v36, 0
	ds_write_b64 v20, v[22:23] offset:20480
	v_fmac_f32_dpp v17, v30, v33 row_newbcast:0 row_mask:0xf bank_mask:0xf bound_ctrl:1
	v_fmac_f32_dpp v16, v30, v33 row_newbcast:1 row_mask:0xf bank_mask:0xf bound_ctrl:1
	v_fmac_f32_dpp v15, v30, v33 row_newbcast:2 row_mask:0xf bank_mask:0xf bound_ctrl:1
	v_fmac_f32_dpp v14, v30, v33 row_newbcast:3 row_mask:0xf bank_mask:0xf bound_ctrl:1
	v_fmac_f32_dpp v13, v30, v33 row_newbcast:4 row_mask:0xf bank_mask:0xf bound_ctrl:1
	v_fmac_f32_dpp v12, v30, v33 row_newbcast:5 row_mask:0xf bank_mask:0xf bound_ctrl:1
	v_fmac_f32_dpp v11, v30, v33 row_newbcast:6 row_mask:0xf bank_mask:0xf bound_ctrl:1
	v_fmac_f32_dpp v10, v30, v33 row_newbcast:7 row_mask:0xf bank_mask:0xf bound_ctrl:1
	v_fmac_f32_dpp v9, v30, v33 row_newbcast:8 row_mask:0xf bank_mask:0xf bound_ctrl:1
	v_fmac_f32_dpp v8, v30, v33 row_newbcast:9 row_mask:0xf bank_mask:0xf bound_ctrl:1
	v_fmac_f32_dpp v7, v30, v33 row_newbcast:10 row_mask:0xf bank_mask:0xf bound_ctrl:1
	v_fmac_f32_dpp v6, v30, v33 row_newbcast:11 row_mask:0xf bank_mask:0xf bound_ctrl:1
	v_fmac_f32_dpp v5, v30, v33 row_newbcast:12 row_mask:0xf bank_mask:0xf bound_ctrl:1
	v_fmac_f32_dpp v4, v30, v33 row_newbcast:13 row_mask:0xf bank_mask:0xf bound_ctrl:1
	v_fmac_f32_dpp v3, v30, v33 row_newbcast:14 row_mask:0xf bank_mask:0xf bound_ctrl:1
	v_fmac_f32_dpp v2, v30, v33 row_newbcast:15 row_mask:0xf bank_mask:0xf bound_ctrl:1
	v_mul_f32_dpp v22, v31, v17 row_newbcast:0 row_mask:0xf bank_mask:0xf bound_ctrl:1
	v_mul_f32_dpp v23, v31, v16 row_newbcast:1 row_mask:0xf bank_mask:0xf bound_ctrl:1
	v_fmac_f32_dpp v22, v31, v15 row_newbcast:2 row_mask:0xf bank_mask:0xf bound_ctrl:1
	v_fmac_f32_dpp v23, v31, v14 row_newbcast:3 row_mask:0xf bank_mask:0xf bound_ctrl:1
	v_fmac_f32_dpp v22, v31, v13 row_newbcast:4 row_mask:0xf bank_mask:0xf bound_ctrl:1
	v_fmac_f32_dpp v23, v31, v12 row_newbcast:5 row_mask:0xf bank_mask:0xf bound_ctrl:1
	v_fmac_f32_dpp v22, v31, v11 row_newbcast:6 row_mask:0xf bank_mask:0xf bound_ctrl:1
	v_fmac_f32_dpp v23, v31, v10 row_newbcast:7 row_mask:0xf bank_mask:0xf bound_ctrl:1
	v_fmac_f32_dpp v22, v31, v9 row_newbcast:8 row_mask:0xf bank_mask:0xf bound_ctrl:1
	v_fmac_f32_dpp v23, v31, v8 row_newbcast:9 row_mask:0xf bank_mask:0xf bound_ctrl:1
	v_fmac_f32_dpp v22, v31, v7 row_newbcast:10 row_mask:0xf bank_mask:0xf bound_ctrl:1
	v_fmac_f32_dpp v23, v31, v6 row_newbcast:11 row_mask:0xf bank_mask:0xf bound_ctrl:1
	v_fmac_f32_dpp v22, v31, v5 row_newbcast:12 row_mask:0xf bank_mask:0xf bound_ctrl:1
	v_fmac_f32_dpp v23, v31, v4 row_newbcast:13 row_mask:0xf bank_mask:0xf bound_ctrl:1
	v_fmac_f32_dpp v22, v31, v3 row_newbcast:14 row_mask:0xf bank_mask:0xf bound_ctrl:1
	v_fmac_f32_dpp v23, v31, v2 row_newbcast:15 row_mask:0xf bank_mask:0xf bound_ctrl:1
	s_waitcnt lgkmcnt(0)
	ds_read_b32 v37, v19 offset:23808
	ds_read2st64_b32 v[28:29], v21 offset0:29 offset1:45
	ds_read2st64_b32 v[30:31], v21 offset0:61 offset1:77
	v_mul_f32_dpp v38, v24, v17 row_newbcast:0 row_mask:0xf bank_mask:0xf bound_ctrl:1
	v_mul_f32_dpp v39, v24, v16 row_newbcast:1 row_mask:0xf bank_mask:0xf bound_ctrl:1
	v_fmac_f32_dpp v38, v24, v15 row_newbcast:2 row_mask:0xf bank_mask:0xf bound_ctrl:1
	v_fmac_f32_dpp v39, v24, v14 row_newbcast:3 row_mask:0xf bank_mask:0xf bound_ctrl:1
	v_fmac_f32_dpp v224, v229, v232 row_newbcast:11 row_mask:0xf bank_mask:0xf bound_ctrl:1
	v_fmac_f32_dpp v38, v24, v13 row_newbcast:4 row_mask:0xf bank_mask:0xf bound_ctrl:1
	v_fmac_f32_dpp v39, v24, v12 row_newbcast:5 row_mask:0xf bank_mask:0xf bound_ctrl:1
	v_fmac_f32_dpp v38, v24, v11 row_newbcast:6 row_mask:0xf bank_mask:0xf bound_ctrl:1
	v_fmac_f32_dpp v39, v24, v10 row_newbcast:7 row_mask:0xf bank_mask:0xf bound_ctrl:1
	v_fmac_f32_dpp v224, v230, v33 row_newbcast:11 row_mask:0xf bank_mask:0xf bound_ctrl:1
	v_fmac_f32_dpp v38, v24, v9 row_newbcast:8 row_mask:0xf bank_mask:0xf bound_ctrl:1
	v_fmac_f32_dpp v39, v24, v8 row_newbcast:9 row_mask:0xf bank_mask:0xf bound_ctrl:1
	v_fmac_f32_dpp v38, v24, v7 row_newbcast:10 row_mask:0xf bank_mask:0xf bound_ctrl:1
	v_fmac_f32_dpp v39, v24, v6 row_newbcast:11 row_mask:0xf bank_mask:0xf bound_ctrl:1
	v_fmac_f32_dpp v38, v24, v5 row_newbcast:12 row_mask:0xf bank_mask:0xf bound_ctrl:1
	v_fmac_f32_dpp v39, v24, v4 row_newbcast:13 row_mask:0xf bank_mask:0xf bound_ctrl:1
	v_fmac_f32_dpp v38, v24, v3 row_newbcast:14 row_mask:0xf bank_mask:0xf bound_ctrl:1
	v_fmac_f32_dpp v39, v24, v2 row_newbcast:15 row_mask:0xf bank_mask:0xf bound_ctrl:1
	v_fmac_f32_dpp v17, v25, v224 row_newbcast:0 row_mask:0xf bank_mask:0xf bound_ctrl:1
	v_fmac_f32_dpp v16, v25, v224 row_newbcast:1 row_mask:0xf bank_mask:0xf bound_ctrl:1
	v_fmac_f32_dpp v15, v25, v224 row_newbcast:2 row_mask:0xf bank_mask:0xf bound_ctrl:1
	v_fmac_f32_dpp v14, v25, v224 row_newbcast:3 row_mask:0xf bank_mask:0xf bound_ctrl:1
	v_fmac_f32_dpp v13, v25, v224 row_newbcast:4 row_mask:0xf bank_mask:0xf bound_ctrl:1
	v_fmac_f32_dpp v12, v25, v224 row_newbcast:5 row_mask:0xf bank_mask:0xf bound_ctrl:1
	v_fmac_f32_dpp v11, v25, v224 row_newbcast:6 row_mask:0xf bank_mask:0xf bound_ctrl:1
	v_fmac_f32_dpp v10, v25, v224 row_newbcast:7 row_mask:0xf bank_mask:0xf bound_ctrl:1
	v_fmac_f32_dpp v9, v25, v224 row_newbcast:8 row_mask:0xf bank_mask:0xf bound_ctrl:1
	v_fmac_f32_dpp v8, v25, v224 row_newbcast:9 row_mask:0xf bank_mask:0xf bound_ctrl:1
	v_fmac_f32_dpp v7, v25, v224 row_newbcast:10 row_mask:0xf bank_mask:0xf bound_ctrl:1
	v_fmac_f32_dpp v6, v25, v224 row_newbcast:11 row_mask:0xf bank_mask:0xf bound_ctrl:1
	v_fmac_f32_dpp v5, v25, v224 row_newbcast:12 row_mask:0xf bank_mask:0xf bound_ctrl:1
	v_fmac_f32_dpp v4, v25, v224 row_newbcast:13 row_mask:0xf bank_mask:0xf bound_ctrl:1
	v_fmac_f32_dpp v3, v25, v224 row_newbcast:14 row_mask:0xf bank_mask:0xf bound_ctrl:1
	v_fmac_f32_dpp v2, v25, v224 row_newbcast:15 row_mask:0xf bank_mask:0xf bound_ctrl:1
	v_add_f32 v38, v38, v39
	s_nop 1
	v_mfma_f32_16x16x4_f32 v[232:235], v228, v38, 0
	ds_write_b64 v20, v[22:23] offset:22528
	v_fmac_f32_dpp v17, v26, v35 row_newbcast:0 row_mask:0xf bank_mask:0xf bound_ctrl:1
	v_fmac_f32_dpp v16, v26, v35 row_newbcast:1 row_mask:0xf bank_mask:0xf bound_ctrl:1
	v_fmac_f32_dpp v15, v26, v35 row_newbcast:2 row_mask:0xf bank_mask:0xf bound_ctrl:1
	v_fmac_f32_dpp v14, v26, v35 row_newbcast:3 row_mask:0xf bank_mask:0xf bound_ctrl:1
	v_fmac_f32_dpp v13, v26, v35 row_newbcast:4 row_mask:0xf bank_mask:0xf bound_ctrl:1
	v_fmac_f32_dpp v12, v26, v35 row_newbcast:5 row_mask:0xf bank_mask:0xf bound_ctrl:1
	v_fmac_f32_dpp v11, v26, v35 row_newbcast:6 row_mask:0xf bank_mask:0xf bound_ctrl:1
	v_fmac_f32_dpp v10, v26, v35 row_newbcast:7 row_mask:0xf bank_mask:0xf bound_ctrl:1
	v_fmac_f32_dpp v9, v26, v35 row_newbcast:8 row_mask:0xf bank_mask:0xf bound_ctrl:1
	v_fmac_f32_dpp v8, v26, v35 row_newbcast:9 row_mask:0xf bank_mask:0xf bound_ctrl:1
	v_fmac_f32_dpp v7, v26, v35 row_newbcast:10 row_mask:0xf bank_mask:0xf bound_ctrl:1
	v_fmac_f32_dpp v6, v26, v35 row_newbcast:11 row_mask:0xf bank_mask:0xf bound_ctrl:1
	v_fmac_f32_dpp v5, v26, v35 row_newbcast:12 row_mask:0xf bank_mask:0xf bound_ctrl:1
	v_fmac_f32_dpp v4, v26, v35 row_newbcast:13 row_mask:0xf bank_mask:0xf bound_ctrl:1
	v_fmac_f32_dpp v3, v26, v35 row_newbcast:14 row_mask:0xf bank_mask:0xf bound_ctrl:1
	v_fmac_f32_dpp v2, v26, v35 row_newbcast:15 row_mask:0xf bank_mask:0xf bound_ctrl:1
	v_mul_f32_dpp v22, v27, v17 row_newbcast:0 row_mask:0xf bank_mask:0xf bound_ctrl:1
	v_mul_f32_dpp v23, v27, v16 row_newbcast:1 row_mask:0xf bank_mask:0xf bound_ctrl:1
	v_fmac_f32_dpp v22, v27, v15 row_newbcast:2 row_mask:0xf bank_mask:0xf bound_ctrl:1
	v_fmac_f32_dpp v23, v27, v14 row_newbcast:3 row_mask:0xf bank_mask:0xf bound_ctrl:1
	v_fmac_f32_dpp v22, v27, v13 row_newbcast:4 row_mask:0xf bank_mask:0xf bound_ctrl:1
	v_fmac_f32_dpp v23, v27, v12 row_newbcast:5 row_mask:0xf bank_mask:0xf bound_ctrl:1
	v_fmac_f32_dpp v22, v27, v11 row_newbcast:6 row_mask:0xf bank_mask:0xf bound_ctrl:1
	v_fmac_f32_dpp v23, v27, v10 row_newbcast:7 row_mask:0xf bank_mask:0xf bound_ctrl:1
	v_fmac_f32_dpp v22, v27, v9 row_newbcast:8 row_mask:0xf bank_mask:0xf bound_ctrl:1
	v_fmac_f32_dpp v23, v27, v8 row_newbcast:9 row_mask:0xf bank_mask:0xf bound_ctrl:1
	v_fmac_f32_dpp v22, v27, v7 row_newbcast:10 row_mask:0xf bank_mask:0xf bound_ctrl:1
	v_fmac_f32_dpp v23, v27, v6 row_newbcast:11 row_mask:0xf bank_mask:0xf bound_ctrl:1
	v_fmac_f32_dpp v22, v27, v5 row_newbcast:12 row_mask:0xf bank_mask:0xf bound_ctrl:1
	v_fmac_f32_dpp v23, v27, v4 row_newbcast:13 row_mask:0xf bank_mask:0xf bound_ctrl:1
	v_fmac_f32_dpp v22, v27, v3 row_newbcast:14 row_mask:0xf bank_mask:0xf bound_ctrl:1
	v_fmac_f32_dpp v23, v27, v2 row_newbcast:15 row_mask:0xf bank_mask:0xf bound_ctrl:1
	s_waitcnt lgkmcnt(0)
	ds_read_b32 v34, v19 offset:24064
	ds_read2st64_b32 v[24:25], v21 offset0:30 offset1:46
	ds_read2st64_b32 v[26:27], v21 offset0:62 offset1:78
	v_mul_f32_dpp v39, v28, v17 row_newbcast:0 row_mask:0xf bank_mask:0xf bound_ctrl:1
	v_mul_f32_dpp v33, v28, v16 row_newbcast:1 row_mask:0xf bank_mask:0xf bound_ctrl:1
	v_fmac_f32_dpp v39, v28, v15 row_newbcast:2 row_mask:0xf bank_mask:0xf bound_ctrl:1
	v_fmac_f32_dpp v33, v28, v14 row_newbcast:3 row_mask:0xf bank_mask:0xf bound_ctrl:1
	v_fmac_f32_dpp v232, v229, v224 row_newbcast:12 row_mask:0xf bank_mask:0xf bound_ctrl:1
	v_fmac_f32_dpp v39, v28, v13 row_newbcast:4 row_mask:0xf bank_mask:0xf bound_ctrl:1
	v_fmac_f32_dpp v33, v28, v12 row_newbcast:5 row_mask:0xf bank_mask:0xf bound_ctrl:1
	v_fmac_f32_dpp v39, v28, v11 row_newbcast:6 row_mask:0xf bank_mask:0xf bound_ctrl:1
	v_fmac_f32_dpp v33, v28, v10 row_newbcast:7 row_mask:0xf bank_mask:0xf bound_ctrl:1
	v_fmac_f32_dpp v232, v230, v35 row_newbcast:12 row_mask:0xf bank_mask:0xf bound_ctrl:1
	v_fmac_f32_dpp v39, v28, v9 row_newbcast:8 row_mask:0xf bank_mask:0xf bound_ctrl:1
	v_fmac_f32_dpp v33, v28, v8 row_newbcast:9 row_mask:0xf bank_mask:0xf bound_ctrl:1
	v_fmac_f32_dpp v39, v28, v7 row_newbcast:10 row_mask:0xf bank_mask:0xf bound_ctrl:1
	v_fmac_f32_dpp v33, v28, v6 row_newbcast:11 row_mask:0xf bank_mask:0xf bound_ctrl:1
	v_fmac_f32_dpp v39, v28, v5 row_newbcast:12 row_mask:0xf bank_mask:0xf bound_ctrl:1
	v_fmac_f32_dpp v33, v28, v4 row_newbcast:13 row_mask:0xf bank_mask:0xf bound_ctrl:1
	v_fmac_f32_dpp v39, v28, v3 row_newbcast:14 row_mask:0xf bank_mask:0xf bound_ctrl:1
	v_fmac_f32_dpp v33, v28, v2 row_newbcast:15 row_mask:0xf bank_mask:0xf bound_ctrl:1
	v_fmac_f32_dpp v17, v29, v232 row_newbcast:0 row_mask:0xf bank_mask:0xf bound_ctrl:1
	v_fmac_f32_dpp v16, v29, v232 row_newbcast:1 row_mask:0xf bank_mask:0xf bound_ctrl:1
	v_fmac_f32_dpp v15, v29, v232 row_newbcast:2 row_mask:0xf bank_mask:0xf bound_ctrl:1
	v_fmac_f32_dpp v14, v29, v232 row_newbcast:3 row_mask:0xf bank_mask:0xf bound_ctrl:1
	v_fmac_f32_dpp v13, v29, v232 row_newbcast:4 row_mask:0xf bank_mask:0xf bound_ctrl:1
	v_fmac_f32_dpp v12, v29, v232 row_newbcast:5 row_mask:0xf bank_mask:0xf bound_ctrl:1
	v_fmac_f32_dpp v11, v29, v232 row_newbcast:6 row_mask:0xf bank_mask:0xf bound_ctrl:1
	v_fmac_f32_dpp v10, v29, v232 row_newbcast:7 row_mask:0xf bank_mask:0xf bound_ctrl:1
	v_fmac_f32_dpp v9, v29, v232 row_newbcast:8 row_mask:0xf bank_mask:0xf bound_ctrl:1
	v_fmac_f32_dpp v8, v29, v232 row_newbcast:9 row_mask:0xf bank_mask:0xf bound_ctrl:1
	v_fmac_f32_dpp v7, v29, v232 row_newbcast:10 row_mask:0xf bank_mask:0xf bound_ctrl:1
	v_fmac_f32_dpp v6, v29, v232 row_newbcast:11 row_mask:0xf bank_mask:0xf bound_ctrl:1
	v_fmac_f32_dpp v5, v29, v232 row_newbcast:12 row_mask:0xf bank_mask:0xf bound_ctrl:1
	v_fmac_f32_dpp v4, v29, v232 row_newbcast:13 row_mask:0xf bank_mask:0xf bound_ctrl:1
	v_fmac_f32_dpp v3, v29, v232 row_newbcast:14 row_mask:0xf bank_mask:0xf bound_ctrl:1
	v_fmac_f32_dpp v2, v29, v232 row_newbcast:15 row_mask:0xf bank_mask:0xf bound_ctrl:1
	v_add_f32 v39, v39, v33
	s_nop 1
	v_mfma_f32_16x16x4_f32 v[224:227], v228, v39, 0
	ds_write_b64 v20, v[22:23] offset:24576
	v_fmac_f32_dpp v17, v30, v37 row_newbcast:0 row_mask:0xf bank_mask:0xf bound_ctrl:1
	v_fmac_f32_dpp v16, v30, v37 row_newbcast:1 row_mask:0xf bank_mask:0xf bound_ctrl:1
	v_fmac_f32_dpp v15, v30, v37 row_newbcast:2 row_mask:0xf bank_mask:0xf bound_ctrl:1
	v_fmac_f32_dpp v14, v30, v37 row_newbcast:3 row_mask:0xf bank_mask:0xf bound_ctrl:1
	v_fmac_f32_dpp v13, v30, v37 row_newbcast:4 row_mask:0xf bank_mask:0xf bound_ctrl:1
	v_fmac_f32_dpp v12, v30, v37 row_newbcast:5 row_mask:0xf bank_mask:0xf bound_ctrl:1
	v_fmac_f32_dpp v11, v30, v37 row_newbcast:6 row_mask:0xf bank_mask:0xf bound_ctrl:1
	v_fmac_f32_dpp v10, v30, v37 row_newbcast:7 row_mask:0xf bank_mask:0xf bound_ctrl:1
	v_fmac_f32_dpp v9, v30, v37 row_newbcast:8 row_mask:0xf bank_mask:0xf bound_ctrl:1
	v_fmac_f32_dpp v8, v30, v37 row_newbcast:9 row_mask:0xf bank_mask:0xf bound_ctrl:1
	v_fmac_f32_dpp v7, v30, v37 row_newbcast:10 row_mask:0xf bank_mask:0xf bound_ctrl:1
	v_fmac_f32_dpp v6, v30, v37 row_newbcast:11 row_mask:0xf bank_mask:0xf bound_ctrl:1
	v_fmac_f32_dpp v5, v30, v37 row_newbcast:12 row_mask:0xf bank_mask:0xf bound_ctrl:1
	v_fmac_f32_dpp v4, v30, v37 row_newbcast:13 row_mask:0xf bank_mask:0xf bound_ctrl:1
	v_fmac_f32_dpp v3, v30, v37 row_newbcast:14 row_mask:0xf bank_mask:0xf bound_ctrl:1
	v_fmac_f32_dpp v2, v30, v37 row_newbcast:15 row_mask:0xf bank_mask:0xf bound_ctrl:1
	v_mul_f32_dpp v28, v31, v17 row_newbcast:0 row_mask:0xf bank_mask:0xf bound_ctrl:1
	v_mul_f32_dpp v29, v31, v16 row_newbcast:1 row_mask:0xf bank_mask:0xf bound_ctrl:1
	v_fmac_f32_dpp v28, v31, v15 row_newbcast:2 row_mask:0xf bank_mask:0xf bound_ctrl:1
	v_fmac_f32_dpp v29, v31, v14 row_newbcast:3 row_mask:0xf bank_mask:0xf bound_ctrl:1
	v_fmac_f32_dpp v28, v31, v13 row_newbcast:4 row_mask:0xf bank_mask:0xf bound_ctrl:1
	v_fmac_f32_dpp v29, v31, v12 row_newbcast:5 row_mask:0xf bank_mask:0xf bound_ctrl:1
	v_fmac_f32_dpp v28, v31, v11 row_newbcast:6 row_mask:0xf bank_mask:0xf bound_ctrl:1
	v_fmac_f32_dpp v29, v31, v10 row_newbcast:7 row_mask:0xf bank_mask:0xf bound_ctrl:1
	v_fmac_f32_dpp v28, v31, v9 row_newbcast:8 row_mask:0xf bank_mask:0xf bound_ctrl:1
	v_fmac_f32_dpp v29, v31, v8 row_newbcast:9 row_mask:0xf bank_mask:0xf bound_ctrl:1
	v_fmac_f32_dpp v28, v31, v7 row_newbcast:10 row_mask:0xf bank_mask:0xf bound_ctrl:1
	v_fmac_f32_dpp v29, v31, v6 row_newbcast:11 row_mask:0xf bank_mask:0xf bound_ctrl:1
	v_fmac_f32_dpp v28, v31, v5 row_newbcast:12 row_mask:0xf bank_mask:0xf bound_ctrl:1
	v_fmac_f32_dpp v29, v31, v4 row_newbcast:13 row_mask:0xf bank_mask:0xf bound_ctrl:1
	v_fmac_f32_dpp v28, v31, v3 row_newbcast:14 row_mask:0xf bank_mask:0xf bound_ctrl:1
	v_fmac_f32_dpp v29, v31, v2 row_newbcast:15 row_mask:0xf bank_mask:0xf bound_ctrl:1
	s_waitcnt lgkmcnt(0)
	ds_read_b32 v19, v19 offset:24320
	ds_read2st64_b32 v[30:31], v21 offset0:31 offset1:47
	ds_read2st64_b32 v[32:33], v21 offset0:63 offset1:79
	v_mul_f32_dpp v22, v24, v17 row_newbcast:0 row_mask:0xf bank_mask:0xf bound_ctrl:1
	v_mul_f32_dpp v35, v24, v16 row_newbcast:1 row_mask:0xf bank_mask:0xf bound_ctrl:1
	v_fmac_f32_dpp v22, v24, v15 row_newbcast:2 row_mask:0xf bank_mask:0xf bound_ctrl:1
	v_fmac_f32_dpp v35, v24, v14 row_newbcast:3 row_mask:0xf bank_mask:0xf bound_ctrl:1
	v_fmac_f32_dpp v224, v229, v232 row_newbcast:13 row_mask:0xf bank_mask:0xf bound_ctrl:1
	v_fmac_f32_dpp v22, v24, v13 row_newbcast:4 row_mask:0xf bank_mask:0xf bound_ctrl:1
	v_fmac_f32_dpp v35, v24, v12 row_newbcast:5 row_mask:0xf bank_mask:0xf bound_ctrl:1
	v_fmac_f32_dpp v22, v24, v11 row_newbcast:6 row_mask:0xf bank_mask:0xf bound_ctrl:1
	v_fmac_f32_dpp v35, v24, v10 row_newbcast:7 row_mask:0xf bank_mask:0xf bound_ctrl:1
	v_fmac_f32_dpp v224, v230, v37 row_newbcast:13 row_mask:0xf bank_mask:0xf bound_ctrl:1
	v_fmac_f32_dpp v22, v24, v9 row_newbcast:8 row_mask:0xf bank_mask:0xf bound_ctrl:1
	v_fmac_f32_dpp v35, v24, v8 row_newbcast:9 row_mask:0xf bank_mask:0xf bound_ctrl:1
	v_fmac_f32_dpp v22, v24, v7 row_newbcast:10 row_mask:0xf bank_mask:0xf bound_ctrl:1
	v_fmac_f32_dpp v35, v24, v6 row_newbcast:11 row_mask:0xf bank_mask:0xf bound_ctrl:1
	v_fmac_f32_dpp v22, v24, v5 row_newbcast:12 row_mask:0xf bank_mask:0xf bound_ctrl:1
	v_fmac_f32_dpp v35, v24, v4 row_newbcast:13 row_mask:0xf bank_mask:0xf bound_ctrl:1
	v_fmac_f32_dpp v22, v24, v3 row_newbcast:14 row_mask:0xf bank_mask:0xf bound_ctrl:1
	v_fmac_f32_dpp v35, v24, v2 row_newbcast:15 row_mask:0xf bank_mask:0xf bound_ctrl:1
	v_fmac_f32_dpp v17, v25, v224 row_newbcast:0 row_mask:0xf bank_mask:0xf bound_ctrl:1
	v_fmac_f32_dpp v16, v25, v224 row_newbcast:1 row_mask:0xf bank_mask:0xf bound_ctrl:1
	v_fmac_f32_dpp v15, v25, v224 row_newbcast:2 row_mask:0xf bank_mask:0xf bound_ctrl:1
	v_fmac_f32_dpp v14, v25, v224 row_newbcast:3 row_mask:0xf bank_mask:0xf bound_ctrl:1
	v_fmac_f32_dpp v13, v25, v224 row_newbcast:4 row_mask:0xf bank_mask:0xf bound_ctrl:1
	v_fmac_f32_dpp v12, v25, v224 row_newbcast:5 row_mask:0xf bank_mask:0xf bound_ctrl:1
	v_fmac_f32_dpp v11, v25, v224 row_newbcast:6 row_mask:0xf bank_mask:0xf bound_ctrl:1
	v_fmac_f32_dpp v10, v25, v224 row_newbcast:7 row_mask:0xf bank_mask:0xf bound_ctrl:1
	v_fmac_f32_dpp v9, v25, v224 row_newbcast:8 row_mask:0xf bank_mask:0xf bound_ctrl:1
	v_fmac_f32_dpp v8, v25, v224 row_newbcast:9 row_mask:0xf bank_mask:0xf bound_ctrl:1
	v_fmac_f32_dpp v7, v25, v224 row_newbcast:10 row_mask:0xf bank_mask:0xf bound_ctrl:1
	v_fmac_f32_dpp v6, v25, v224 row_newbcast:11 row_mask:0xf bank_mask:0xf bound_ctrl:1
	v_fmac_f32_dpp v5, v25, v224 row_newbcast:12 row_mask:0xf bank_mask:0xf bound_ctrl:1
	v_fmac_f32_dpp v4, v25, v224 row_newbcast:13 row_mask:0xf bank_mask:0xf bound_ctrl:1
	v_fmac_f32_dpp v3, v25, v224 row_newbcast:14 row_mask:0xf bank_mask:0xf bound_ctrl:1
	v_fmac_f32_dpp v2, v25, v224 row_newbcast:15 row_mask:0xf bank_mask:0xf bound_ctrl:1
	v_add_f32 v22, v22, v35
	s_nop 1
	v_mfma_f32_16x16x4_f32 v[232:235], v228, v22, 0
	ds_write_b64 v20, v[28:29] offset:26624
	v_fmac_f32_dpp v17, v26, v34 row_newbcast:0 row_mask:0xf bank_mask:0xf bound_ctrl:1
	v_fmac_f32_dpp v16, v26, v34 row_newbcast:1 row_mask:0xf bank_mask:0xf bound_ctrl:1
	v_fmac_f32_dpp v15, v26, v34 row_newbcast:2 row_mask:0xf bank_mask:0xf bound_ctrl:1
	v_fmac_f32_dpp v14, v26, v34 row_newbcast:3 row_mask:0xf bank_mask:0xf bound_ctrl:1
	v_fmac_f32_dpp v13, v26, v34 row_newbcast:4 row_mask:0xf bank_mask:0xf bound_ctrl:1
	v_fmac_f32_dpp v12, v26, v34 row_newbcast:5 row_mask:0xf bank_mask:0xf bound_ctrl:1
	v_fmac_f32_dpp v11, v26, v34 row_newbcast:6 row_mask:0xf bank_mask:0xf bound_ctrl:1
	v_fmac_f32_dpp v10, v26, v34 row_newbcast:7 row_mask:0xf bank_mask:0xf bound_ctrl:1
	v_fmac_f32_dpp v9, v26, v34 row_newbcast:8 row_mask:0xf bank_mask:0xf bound_ctrl:1
	v_fmac_f32_dpp v8, v26, v34 row_newbcast:9 row_mask:0xf bank_mask:0xf bound_ctrl:1
	v_fmac_f32_dpp v7, v26, v34 row_newbcast:10 row_mask:0xf bank_mask:0xf bound_ctrl:1
	v_fmac_f32_dpp v6, v26, v34 row_newbcast:11 row_mask:0xf bank_mask:0xf bound_ctrl:1
	v_fmac_f32_dpp v5, v26, v34 row_newbcast:12 row_mask:0xf bank_mask:0xf bound_ctrl:1
	v_fmac_f32_dpp v4, v26, v34 row_newbcast:13 row_mask:0xf bank_mask:0xf bound_ctrl:1
	v_fmac_f32_dpp v3, v26, v34 row_newbcast:14 row_mask:0xf bank_mask:0xf bound_ctrl:1
	v_fmac_f32_dpp v2, v26, v34 row_newbcast:15 row_mask:0xf bank_mask:0xf bound_ctrl:1
	v_mul_f32_dpp v24, v27, v17 row_newbcast:0 row_mask:0xf bank_mask:0xf bound_ctrl:1
	v_mul_f32_dpp v25, v27, v16 row_newbcast:1 row_mask:0xf bank_mask:0xf bound_ctrl:1
	v_fmac_f32_dpp v24, v27, v15 row_newbcast:2 row_mask:0xf bank_mask:0xf bound_ctrl:1
	v_fmac_f32_dpp v25, v27, v14 row_newbcast:3 row_mask:0xf bank_mask:0xf bound_ctrl:1
	v_fmac_f32_dpp v24, v27, v13 row_newbcast:4 row_mask:0xf bank_mask:0xf bound_ctrl:1
	v_fmac_f32_dpp v25, v27, v12 row_newbcast:5 row_mask:0xf bank_mask:0xf bound_ctrl:1
	v_fmac_f32_dpp v24, v27, v11 row_newbcast:6 row_mask:0xf bank_mask:0xf bound_ctrl:1
	v_fmac_f32_dpp v25, v27, v10 row_newbcast:7 row_mask:0xf bank_mask:0xf bound_ctrl:1
	v_fmac_f32_dpp v24, v27, v9 row_newbcast:8 row_mask:0xf bank_mask:0xf bound_ctrl:1
	v_fmac_f32_dpp v25, v27, v8 row_newbcast:9 row_mask:0xf bank_mask:0xf bound_ctrl:1
	v_fmac_f32_dpp v24, v27, v7 row_newbcast:10 row_mask:0xf bank_mask:0xf bound_ctrl:1
	v_fmac_f32_dpp v25, v27, v6 row_newbcast:11 row_mask:0xf bank_mask:0xf bound_ctrl:1
	v_fmac_f32_dpp v24, v27, v5 row_newbcast:12 row_mask:0xf bank_mask:0xf bound_ctrl:1
	v_fmac_f32_dpp v25, v27, v4 row_newbcast:13 row_mask:0xf bank_mask:0xf bound_ctrl:1
	v_fmac_f32_dpp v24, v27, v3 row_newbcast:14 row_mask:0xf bank_mask:0xf bound_ctrl:1
	v_fmac_f32_dpp v25, v27, v2 row_newbcast:15 row_mask:0xf bank_mask:0xf bound_ctrl:1
	s_waitcnt lgkmcnt(0)
	v_mul_f32_dpp v18, v30, v17 row_newbcast:0 row_mask:0xf bank_mask:0xf bound_ctrl:1
	v_mul_f32_dpp v27, v30, v16 row_newbcast:1 row_mask:0xf bank_mask:0xf bound_ctrl:1
	v_fmac_f32_dpp v18, v30, v15 row_newbcast:2 row_mask:0xf bank_mask:0xf bound_ctrl:1
	v_fmac_f32_dpp v27, v30, v14 row_newbcast:3 row_mask:0xf bank_mask:0xf bound_ctrl:1
	v_fmac_f32_dpp v18, v30, v13 row_newbcast:4 row_mask:0xf bank_mask:0xf bound_ctrl:1
	v_fmac_f32_dpp v27, v30, v12 row_newbcast:5 row_mask:0xf bank_mask:0xf bound_ctrl:1
	v_fmac_f32_dpp v18, v30, v11 row_newbcast:6 row_mask:0xf bank_mask:0xf bound_ctrl:1
	v_fmac_f32_dpp v27, v30, v10 row_newbcast:7 row_mask:0xf bank_mask:0xf bound_ctrl:1
	v_fmac_f32_dpp v232, v229, v224 row_newbcast:14 row_mask:0xf bank_mask:0xf bound_ctrl:1
	v_fmac_f32_dpp v18, v30, v9 row_newbcast:8 row_mask:0xf bank_mask:0xf bound_ctrl:1
	v_fmac_f32_dpp v27, v30, v8 row_newbcast:9 row_mask:0xf bank_mask:0xf bound_ctrl:1
	v_fmac_f32_dpp v18, v30, v7 row_newbcast:10 row_mask:0xf bank_mask:0xf bound_ctrl:1
	v_fmac_f32_dpp v27, v30, v6 row_newbcast:11 row_mask:0xf bank_mask:0xf bound_ctrl:1
	v_fmac_f32_dpp v232, v230, v34 row_newbcast:14 row_mask:0xf bank_mask:0xf bound_ctrl:1
	v_fmac_f32_dpp v18, v30, v5 row_newbcast:12 row_mask:0xf bank_mask:0xf bound_ctrl:1
	v_fmac_f32_dpp v27, v30, v4 row_newbcast:13 row_mask:0xf bank_mask:0xf bound_ctrl:1
	v_fmac_f32_dpp v18, v30, v3 row_newbcast:14 row_mask:0xf bank_mask:0xf bound_ctrl:1
	v_fmac_f32_dpp v27, v30, v2 row_newbcast:15 row_mask:0xf bank_mask:0xf bound_ctrl:1
	v_fmac_f32_dpp v17, v31, v232 row_newbcast:0 row_mask:0xf bank_mask:0xf bound_ctrl:1
	v_fmac_f32_dpp v16, v31, v232 row_newbcast:1 row_mask:0xf bank_mask:0xf bound_ctrl:1
	v_fmac_f32_dpp v15, v31, v232 row_newbcast:2 row_mask:0xf bank_mask:0xf bound_ctrl:1
	v_fmac_f32_dpp v14, v31, v232 row_newbcast:3 row_mask:0xf bank_mask:0xf bound_ctrl:1
	v_fmac_f32_dpp v13, v31, v232 row_newbcast:4 row_mask:0xf bank_mask:0xf bound_ctrl:1
	v_fmac_f32_dpp v12, v31, v232 row_newbcast:5 row_mask:0xf bank_mask:0xf bound_ctrl:1
	v_fmac_f32_dpp v11, v31, v232 row_newbcast:6 row_mask:0xf bank_mask:0xf bound_ctrl:1
	v_fmac_f32_dpp v10, v31, v232 row_newbcast:7 row_mask:0xf bank_mask:0xf bound_ctrl:1
	v_fmac_f32_dpp v9, v31, v232 row_newbcast:8 row_mask:0xf bank_mask:0xf bound_ctrl:1
	v_fmac_f32_dpp v8, v31, v232 row_newbcast:9 row_mask:0xf bank_mask:0xf bound_ctrl:1
	v_fmac_f32_dpp v7, v31, v232 row_newbcast:10 row_mask:0xf bank_mask:0xf bound_ctrl:1
	v_fmac_f32_dpp v6, v31, v232 row_newbcast:11 row_mask:0xf bank_mask:0xf bound_ctrl:1
	v_fmac_f32_dpp v5, v31, v232 row_newbcast:12 row_mask:0xf bank_mask:0xf bound_ctrl:1
	v_fmac_f32_dpp v4, v31, v232 row_newbcast:13 row_mask:0xf bank_mask:0xf bound_ctrl:1
	v_fmac_f32_dpp v3, v31, v232 row_newbcast:14 row_mask:0xf bank_mask:0xf bound_ctrl:1
	v_fmac_f32_dpp v2, v31, v232 row_newbcast:15 row_mask:0xf bank_mask:0xf bound_ctrl:1
	v_add_f32 v18, v18, v27
	s_nop 1
	v_mfma_f32_16x16x4_f32 v[224:227], v228, v18, 0
	ds_write_b64 v20, v[24:25] offset:28672
	ds_read_b32 v21, v21 offset:3840
	v_fmac_f32_dpp v17, v32, v19 row_newbcast:0 row_mask:0xf bank_mask:0xf bound_ctrl:1
	v_fmac_f32_dpp v16, v32, v19 row_newbcast:1 row_mask:0xf bank_mask:0xf bound_ctrl:1
	v_fmac_f32_dpp v15, v32, v19 row_newbcast:2 row_mask:0xf bank_mask:0xf bound_ctrl:1
	v_fmac_f32_dpp v14, v32, v19 row_newbcast:3 row_mask:0xf bank_mask:0xf bound_ctrl:1
	v_fmac_f32_dpp v13, v32, v19 row_newbcast:4 row_mask:0xf bank_mask:0xf bound_ctrl:1
	v_fmac_f32_dpp v12, v32, v19 row_newbcast:5 row_mask:0xf bank_mask:0xf bound_ctrl:1
	v_fmac_f32_dpp v11, v32, v19 row_newbcast:6 row_mask:0xf bank_mask:0xf bound_ctrl:1
	v_fmac_f32_dpp v10, v32, v19 row_newbcast:7 row_mask:0xf bank_mask:0xf bound_ctrl:1
	v_fmac_f32_dpp v9, v32, v19 row_newbcast:8 row_mask:0xf bank_mask:0xf bound_ctrl:1
	v_fmac_f32_dpp v8, v32, v19 row_newbcast:9 row_mask:0xf bank_mask:0xf bound_ctrl:1
	v_fmac_f32_dpp v7, v32, v19 row_newbcast:10 row_mask:0xf bank_mask:0xf bound_ctrl:1
	v_fmac_f32_dpp v6, v32, v19 row_newbcast:11 row_mask:0xf bank_mask:0xf bound_ctrl:1
	v_fmac_f32_dpp v5, v32, v19 row_newbcast:12 row_mask:0xf bank_mask:0xf bound_ctrl:1
	v_fmac_f32_dpp v4, v32, v19 row_newbcast:13 row_mask:0xf bank_mask:0xf bound_ctrl:1
	v_fmac_f32_dpp v3, v32, v19 row_newbcast:14 row_mask:0xf bank_mask:0xf bound_ctrl:1
	v_fmac_f32_dpp v2, v32, v19 row_newbcast:15 row_mask:0xf bank_mask:0xf bound_ctrl:1
	v_mul_f32_dpp v24, v33, v17 row_newbcast:0 row_mask:0xf bank_mask:0xf bound_ctrl:1
	v_mul_f32_dpp v25, v33, v16 row_newbcast:1 row_mask:0xf bank_mask:0xf bound_ctrl:1
	v_fmac_f32_dpp v24, v33, v15 row_newbcast:2 row_mask:0xf bank_mask:0xf bound_ctrl:1
	v_fmac_f32_dpp v25, v33, v14 row_newbcast:3 row_mask:0xf bank_mask:0xf bound_ctrl:1
	v_fmac_f32_dpp v24, v33, v13 row_newbcast:4 row_mask:0xf bank_mask:0xf bound_ctrl:1
	v_fmac_f32_dpp v25, v33, v12 row_newbcast:5 row_mask:0xf bank_mask:0xf bound_ctrl:1
	v_fmac_f32_dpp v24, v33, v11 row_newbcast:6 row_mask:0xf bank_mask:0xf bound_ctrl:1
	v_fmac_f32_dpp v25, v33, v10 row_newbcast:7 row_mask:0xf bank_mask:0xf bound_ctrl:1
	v_fmac_f32_dpp v24, v33, v9 row_newbcast:8 row_mask:0xf bank_mask:0xf bound_ctrl:1
	v_fmac_f32_dpp v25, v33, v8 row_newbcast:9 row_mask:0xf bank_mask:0xf bound_ctrl:1
	v_fmac_f32_dpp v24, v33, v7 row_newbcast:10 row_mask:0xf bank_mask:0xf bound_ctrl:1
	v_fmac_f32_dpp v25, v33, v6 row_newbcast:11 row_mask:0xf bank_mask:0xf bound_ctrl:1
	v_fmac_f32_dpp v24, v33, v5 row_newbcast:12 row_mask:0xf bank_mask:0xf bound_ctrl:1
	v_fmac_f32_dpp v25, v33, v4 row_newbcast:13 row_mask:0xf bank_mask:0xf bound_ctrl:1
	v_fmac_f32_dpp v24, v33, v3 row_newbcast:14 row_mask:0xf bank_mask:0xf bound_ctrl:1
	v_fmac_f32_dpp v25, v33, v2 row_newbcast:15 row_mask:0xf bank_mask:0xf bound_ctrl:1
	s_waitcnt lgkmcnt(0)
	v_mul_f32_dpp v17, v21, v17 row_newbcast:0 row_mask:0xf bank_mask:0xf bound_ctrl:1
	v_mul_f32_dpp v16, v21, v16 row_newbcast:1 row_mask:0xf bank_mask:0xf bound_ctrl:1
	v_mul_f32_dpp v15, v21, v15 row_newbcast:2 row_mask:0xf bank_mask:0xf bound_ctrl:1
	v_mul_f32_dpp v14, v21, v14 row_newbcast:3 row_mask:0xf bank_mask:0xf bound_ctrl:1
	v_mul_f32_dpp v13, v21, v13 row_newbcast:4 row_mask:0xf bank_mask:0xf bound_ctrl:1
	v_mul_f32_dpp v12, v21, v12 row_newbcast:5 row_mask:0xf bank_mask:0xf bound_ctrl:1
	v_mul_f32_dpp v11, v21, v11 row_newbcast:6 row_mask:0xf bank_mask:0xf bound_ctrl:1
	v_mul_f32_dpp v10, v21, v10 row_newbcast:7 row_mask:0xf bank_mask:0xf bound_ctrl:1
	v_mul_f32_dpp v9, v21, v9 row_newbcast:8 row_mask:0xf bank_mask:0xf bound_ctrl:1
	v_mul_f32_dpp v8, v21, v8 row_newbcast:9 row_mask:0xf bank_mask:0xf bound_ctrl:1
	v_mul_f32_dpp v7, v21, v7 row_newbcast:10 row_mask:0xf bank_mask:0xf bound_ctrl:1
	v_mul_f32_dpp v6, v21, v6 row_newbcast:11 row_mask:0xf bank_mask:0xf bound_ctrl:1
	v_mul_f32_dpp v5, v21, v5 row_newbcast:12 row_mask:0xf bank_mask:0xf bound_ctrl:1
	v_mul_f32_dpp v4, v21, v4 row_newbcast:13 row_mask:0xf bank_mask:0xf bound_ctrl:1
	v_mul_f32_dpp v3, v21, v3 row_newbcast:14 row_mask:0xf bank_mask:0xf bound_ctrl:1
	v_mul_f32_dpp v2, v21, v2 row_newbcast:15 row_mask:0xf bank_mask:0xf bound_ctrl:1
	ds_write_b64 v20, v[24:25] offset:30720
	s_waitcnt lgkmcnt(0)
	s_barrier
	s_cbranch_scc1 .LBB0_583
